# re-stagger rendezvous taken after the next unit's index math and accumulator zeroing (flag in s100), on top of prologue hoist
# baseline (speedup 1.0000x reference)
_Z10fwd_kernel4Args:
	s_mov_b32 s100, 0
	s_load_dwordx4 s[92:95], s[0:1], 0xc0
	s_load_dword s3, s[0:1], 0xd0
	s_add_u32 s4, s0, 0xd0
	s_addc_u32 s5, s1, 0
	v_cmp_gt_u32_e32 vcc, 32, v0
	s_waitcnt lgkmcnt(0)
	v_writelane_b32 v253, s3, 0
	v_writelane_b32 v253, s4, 1
	s_nop 1
	v_writelane_b32 v253, s5, 2
	s_and_saveexec_b64 s[4:5], vcc
	v_lshl_add_u32 v1, v0, 2, 0
	v_add_u32_e32 v1, 0x21000, v1
	v_mov_b32_e32 v2, 0
	ds_write_b32 v1, v2
	s_or_b64 exec, exec, s[4:5]
	s_waitcnt lgkmcnt(0)
	s_barrier
	s_add_u32 s14, s94, 0x4000
	s_getreg_b32 s3, hwreg(HW_REG_XCC_ID, 0, 4)
	s_addc_u32 s15, s95, 0
	s_and_b32 s3, s3, 15
	s_lshl_b32 s33, s3, 6
	v_cmp_eq_u32_e64 s[6:7], 0, v0
	s_mov_b64 s[4:5], exec
	s_nop 0
	v_writelane_b32 v253, s6, 3
	s_nop 1
	v_writelane_b32 v253, s7, 4
	s_and_b64 s[6:7], s[4:5], s[6:7]
	s_mov_b64 exec, s[6:7]
	s_cbranch_execz .LBB0_5
	s_mov_b64 s[6:7], exec
	v_mbcnt_lo_u32_b32 v1, s6, 0
	v_mbcnt_hi_u32_b32 v1, s7, v1
	v_cmp_eq_u32_e32 vcc, 0, v1
	s_and_b64 s[8:9], exec, vcc
	s_mov_b64 exec, s[8:9]
	s_cbranch_execz .LBB0_5
	s_lshl_b32 s8, s33, 2
	s_bcnt1_i32_b64 s6, s[6:7]
	v_mov_b32_e32 v1, s8
	v_mov_b32_e32 v2, s6
	global_atomic_add v1, v2, s[14:15] offset:1024

.LBB0_245:
	s_ashr_i32 s69, s68, 31
	s_lshl_b64 s[56:57], s[68:69], 20
	s_add_u32 s33, s14, s56
	s_addc_u32 s48, s15, s57
	s_ashr_i32 s75, s74, 31
	s_lshl_b64 s[56:57], s[74:75], 7
	s_add_u32 s84, s33, s56
	s_addc_u32 s85, s48, s57
	s_and_b64 s[76:77], s[90:91], exec
	s_cselect_b32 s69, s85, s1
	s_cselect_b32 s75, s84, s0
	s_ashr_i32 s73, s72, 31
	s_lshl_b64 s[76:77], s[72:73], 20
	s_add_u32 s33, s9, s76
	s_addc_u32 s48, s23, s77
	s_add_u32 s86, s33, s56
	s_addc_u32 s87, s48, s57
	s_and_b64 s[56:57], s[90:91], exec
	s_cselect_b32 s73, s87, s89
	s_cselect_b32 vcc_lo, s86, s88
	s_add_i32 vcc_hi, s55, -2
	s_add_u32 s0, s0, 0x80080
	s_addc_u32 s1, s1, 0
	s_add_u32 s56, s88, 0x100
	s_addc_u32 s57, s89, 0
	s_mov_b32 s88, 0
	v_mov_b64_e32 v[4:5], 0
	v_mov_b64_e32 v[6:7], 0
	v_mov_b64_e32 v[8:9], 0
	v_mov_b64_e32 v[10:11], 0
	v_mov_b64_e32 v[12:13], 0
	v_mov_b64_e32 v[14:15], 0
	v_mov_b64_e32 v[16:17], 0
	v_mov_b64_e32 v[18:19], 0
	v_mov_b64_e32 v[20:21], 0
	v_mov_b64_e32 v[22:23], 0
	v_mov_b64_e32 v[24:25], 0
	v_mov_b64_e32 v[26:27], 0
	v_mov_b64_e32 v[28:29], 0
	v_mov_b64_e32 v[30:31], 0
	v_mov_b64_e32 v[32:33], 0
	v_mov_b64_e32 v[34:35], 0
	v_mov_b64_e32 v[36:37], 0
	v_mov_b64_e32 v[38:39], 0
	v_mov_b64_e32 v[40:41], 0
	v_mov_b64_e32 v[42:43], 0
	v_mov_b64_e32 v[44:45], 0
	v_mov_b64_e32 v[46:47], 0
	v_mov_b64_e32 v[48:49], 0
	v_mov_b64_e32 v[50:51], 0
	v_mov_b64_e32 v[52:53], 0
	v_mov_b64_e32 v[54:55], 0
	v_mov_b64_e32 v[56:57], 0
	v_mov_b64_e32 v[58:59], 0
	v_mov_b64_e32 v[60:61], 0
	v_mov_b64_e32 v[62:63], 0
	v_mov_b64_e32 v[64:65], 0
	v_mov_b64_e32 v[66:67], 0
	v_mov_b64_e32 v[68:69], 0
	v_mov_b64_e32 v[70:71], 0
	v_mov_b64_e32 v[72:73], 0
	v_mov_b64_e32 v[74:75], 0
	v_mov_b64_e32 v[76:77], 0
	v_mov_b64_e32 v[78:79], 0
	v_mov_b64_e32 v[80:81], 0
	v_mov_b64_e32 v[82:83], 0
	v_mov_b64_e32 v[84:85], 0
	v_mov_b64_e32 v[86:87], 0
	v_mov_b64_e32 v[88:89], 0
	v_mov_b64_e32 v[90:91], 0
	v_mov_b64_e32 v[92:93], 0
	v_mov_b64_e32 v[94:95], 0
	v_mov_b64_e32 v[96:97], 0
	v_mov_b64_e32 v[98:99], 0
	v_mov_b64_e32 v[100:101], 0
	v_mov_b64_e32 v[102:103], 0
	v_mov_b64_e32 v[104:105], 0
	v_mov_b64_e32 v[106:107], 0
	v_mov_b64_e32 v[108:109], 0
	v_mov_b64_e32 v[110:111], 0
	v_mov_b64_e32 v[112:113], 0
	v_mov_b64_e32 v[114:115], 0
	v_mov_b64_e32 v[116:117], 0
	v_mov_b64_e32 v[118:119], 0
	v_mov_b64_e32 v[120:121], 0
	v_mov_b64_e32 v[122:123], 0
	v_mov_b64_e32 v[124:125], 0
	v_mov_b64_e32 v[126:127], 0
	v_mov_b64_e32 v[128:129], 0
	v_mov_b64_e32 v[130:131], 0
	v_add_u32_e32 v246, 0x10000, v1
	v_add_u32_e32 v247, 0x14000, v1
	v_add_u32_e32 v248, 0x18000, v1
	v_add_u32_e32 v249, 0x1c000, v1
	s_cmp_eq_u32 s100, 0
	s_cbranch_scc1 .Lrs1
	s_barrier
	s_mov_b32 s100, 0
.Lrs1:
.LBB0_246:
	s_add_i32 s76, s88, 2
	s_add_u32 s33, s0, 0xfff80080
	s_addc_u32 s48, s1, -1
	s_add_i32 m0, s35, 0xc000
	s_add_i32 s77, s35, 0xe000
	global_load_lds_dwordx4 v146, s[0:1]
	s_mov_b32 m0, s77
	s_cmp_eq_u32 vcc_hi, s88
	global_load_lds_dwordx4 v148, s[0:1]
	s_cselect_b32 s88, vcc_lo, s56
	s_cselect_b32 s91, s69, s48
	s_cselect_b32 s90, s75, s33
	s_cselect_b32 s89, s73, s57
	s_add_i32 s33, 0, 0x10000
	s_add_i32 s96, 0, 0x14000
	ds_read_b128 v[150:153], v246
	ds_read_b128 v[154:157], v246 offset:1024
	ds_read_b128 v[158:161], v246 offset:2048
	ds_read_b128 v[162:165], v246 offset:3072
	ds_read_b128 v[166:169], v247
	ds_read_b128 v[170:173], v247 offset:1024
	ds_read_b128 v[174:177], v247 offset:2048
	ds_read_b128 v[178:181], v247 offset:3072
	ds_read_b128 v[182:185], v141
	ds_read_b128 v[186:189], v141 offset:1024
	ds_read_b128 v[190:193], v141 offset:2048
	ds_read_b128 v[194:197], v141 offset:3072
	ds_read_b128 v[198:201], v141 offset:4096
	ds_read_b128 v[202:205], v141 offset:5120
	ds_read_b128 v[210:213], v141 offset:6144
	ds_read_b128 v[214:217], v141 offset:7168
	s_waitcnt vmcnt(8)
	s_waitcnt lgkmcnt(0)
	s_setprio 1
	s_barrier
	v_mfma_f32_16x16x32_bf16 v[128:131], v[150:153], v[182:185], v[128:131]
	v_mfma_f32_16x16x32_bf16 v[124:127], v[158:161], v[182:185], v[124:127]
	v_mfma_f32_16x16x32_bf16 v[116:119], v[150:153], v[190:193], v[116:119]
	v_mfma_f32_16x16x32_bf16 v[108:111], v[158:161], v[190:193], v[108:111]
	v_mfma_f32_16x16x32_bf16 v[100:103], v[150:153], v[198:201], v[100:103]
	v_mfma_f32_16x16x32_bf16 v[92:95], v[158:161], v[198:201], v[92:95]
	v_mfma_f32_16x16x32_bf16 v[84:87], v[150:153], v[210:213], v[84:87]
	v_mfma_f32_16x16x32_bf16 v[76:79], v[158:161], v[210:213], v[76:79]
	v_mfma_f32_16x16x32_bf16 v[128:131], v[154:157], v[186:189], v[128:131]
	v_mfma_f32_16x16x32_bf16 v[124:127], v[162:165], v[186:189], v[124:127]
	v_mfma_f32_16x16x32_bf16 v[116:119], v[154:157], v[194:197], v[116:119]
	v_mfma_f32_16x16x32_bf16 v[108:111], v[162:165], v[194:197], v[108:111]
	v_mfma_f32_16x16x32_bf16 v[100:103], v[154:157], v[202:205], v[100:103]
	v_mfma_f32_16x16x32_bf16 v[92:95], v[162:165], v[202:205], v[92:95]
	v_mfma_f32_16x16x32_bf16 v[84:87], v[154:157], v[214:217], v[84:87]
	v_mfma_f32_16x16x32_bf16 v[76:79], v[162:165], v[214:217], v[76:79]
	v_mfma_f32_16x16x32_bf16 v[120:123], v[166:169], v[182:185], v[120:123]
	v_mfma_f32_16x16x32_bf16 v[112:115], v[174:177], v[182:185], v[112:115]
	v_mfma_f32_16x16x32_bf16 v[104:107], v[166:169], v[190:193], v[104:107]
	v_mfma_f32_16x16x32_bf16 v[96:99], v[174:177], v[190:193], v[96:99]
	v_mfma_f32_16x16x32_bf16 v[88:91], v[166:169], v[198:201], v[88:91]
	v_mfma_f32_16x16x32_bf16 v[80:83], v[174:177], v[198:201], v[80:83]
	v_mfma_f32_16x16x32_bf16 v[72:75], v[166:169], v[210:213], v[72:75]
	v_mfma_f32_16x16x32_bf16 v[68:71], v[174:177], v[210:213], v[68:71]
	v_mfma_f32_16x16x32_bf16 v[120:123], v[170:173], v[186:189], v[120:123]
	v_mfma_f32_16x16x32_bf16 v[112:115], v[178:181], v[186:189], v[112:115]
	v_mfma_f32_16x16x32_bf16 v[104:107], v[170:173], v[194:197], v[104:107]
	v_mfma_f32_16x16x32_bf16 v[96:99], v[178:181], v[194:197], v[96:99]
	v_mfma_f32_16x16x32_bf16 v[88:91], v[170:173], v[202:205], v[88:91]
	v_mfma_f32_16x16x32_bf16 v[80:83], v[178:181], v[202:205], v[80:83]
	v_mfma_f32_16x16x32_bf16 v[72:75], v[170:173], v[214:217], v[72:75]
	v_mfma_f32_16x16x32_bf16 v[68:71], v[178:181], v[214:217], v[68:71]
	s_barrier
	s_setprio 0
	s_add_i32 s48, s33, s29
	s_mov_b32 m0, s48
	s_nop 0
	global_load_lds_dwordx4 v134, s[88:89]
	s_add_i32 m0, s48, 0x2000
	s_add_u32 s78, s88, 0x80000
	s_addc_u32 s79, s89, 0
	s_add_i32 s48, s96, s29
	global_load_lds_dwordx4 v138, s[88:89]
	s_mov_b32 m0, s48
	s_nop 0
	global_load_lds_dwordx4 v134, s[78:79]
	s_add_i32 m0, s48, 0x2000
	s_nop 0
	global_load_lds_dwordx4 v138, s[78:79]
	s_mov_b32 m0, s35
	s_nop 0
	global_load_lds_dwordx4 v132, s[90:91]
	s_mov_b32 m0, s60
	s_nop 0
	global_load_lds_dwordx4 v136, s[90:91]
	ds_read_b128 v[182:185], v141 offset:16384
	ds_read_b128 v[186:189], v141 offset:17408
	ds_read_b128 v[190:193], v141 offset:18432
	ds_read_b128 v[194:197], v141 offset:19456
	ds_read_b128 v[198:201], v141 offset:20480
	ds_read_b128 v[202:205], v141 offset:21504
	ds_read_b128 v[210:213], v141 offset:22528
	ds_read_b128 v[214:217], v141 offset:23552
	s_waitcnt vmcnt(8)
	s_waitcnt lgkmcnt(0)
	s_setprio 1
	s_barrier
	v_mfma_f32_16x16x32_bf16 v[64:67], v[150:153], v[182:185], v[64:67]
	v_mfma_f32_16x16x32_bf16 v[60:63], v[158:161], v[182:185], v[60:63]
	v_mfma_f32_16x16x32_bf16 v[52:55], v[150:153], v[190:193], v[52:55]
	v_mfma_f32_16x16x32_bf16 v[44:47], v[158:161], v[190:193], v[44:47]
	v_mfma_f32_16x16x32_bf16 v[36:39], v[150:153], v[198:201], v[36:39]
	v_mfma_f32_16x16x32_bf16 v[28:31], v[158:161], v[198:201], v[28:31]
	v_mfma_f32_16x16x32_bf16 v[20:23], v[150:153], v[210:213], v[20:23]
	v_mfma_f32_16x16x32_bf16 v[12:15], v[158:161], v[210:213], v[12:15]
	v_mfma_f32_16x16x32_bf16 v[64:67], v[154:157], v[186:189], v[64:67]
	v_mfma_f32_16x16x32_bf16 v[60:63], v[162:165], v[186:189], v[60:63]
	v_mfma_f32_16x16x32_bf16 v[52:55], v[154:157], v[194:197], v[52:55]
	v_mfma_f32_16x16x32_bf16 v[44:47], v[162:165], v[194:197], v[44:47]
	v_mfma_f32_16x16x32_bf16 v[36:39], v[154:157], v[202:205], v[36:39]
	v_mfma_f32_16x16x32_bf16 v[28:31], v[162:165], v[202:205], v[28:31]
	v_mfma_f32_16x16x32_bf16 v[20:23], v[154:157], v[214:217], v[20:23]
	v_mfma_f32_16x16x32_bf16 v[12:15], v[162:165], v[214:217], v[12:15]
	v_mfma_f32_16x16x32_bf16 v[56:59], v[166:169], v[182:185], v[56:59]
	v_mfma_f32_16x16x32_bf16 v[48:51], v[174:177], v[182:185], v[48:51]
	v_mfma_f32_16x16x32_bf16 v[40:43], v[166:169], v[190:193], v[40:43]
	v_mfma_f32_16x16x32_bf16 v[32:35], v[174:177], v[190:193], v[32:35]
	v_mfma_f32_16x16x32_bf16 v[24:27], v[166:169], v[198:201], v[24:27]
	v_mfma_f32_16x16x32_bf16 v[16:19], v[174:177], v[198:201], v[16:19]
	v_mfma_f32_16x16x32_bf16 v[8:11], v[166:169], v[210:213], v[8:11]
	v_mfma_f32_16x16x32_bf16 v[4:7], v[174:177], v[210:213], v[4:7]
	v_mfma_f32_16x16x32_bf16 v[56:59], v[170:173], v[186:189], v[56:59]
	v_mfma_f32_16x16x32_bf16 v[48:51], v[178:181], v[186:189], v[48:51]
	v_mfma_f32_16x16x32_bf16 v[40:43], v[170:173], v[194:197], v[40:43]
	v_mfma_f32_16x16x32_bf16 v[32:35], v[178:181], v[194:197], v[32:35]
	v_mfma_f32_16x16x32_bf16 v[24:27], v[170:173], v[202:205], v[24:27]
	v_mfma_f32_16x16x32_bf16 v[16:19], v[178:181], v[202:205], v[16:19]
	v_mfma_f32_16x16x32_bf16 v[8:11], v[170:173], v[214:217], v[8:11]
	v_mfma_f32_16x16x32_bf16 v[4:7], v[178:181], v[214:217], v[4:7]
	s_barrier
	s_setprio 0
	s_add_u32 s78, s90, 0x80000
	s_addc_u32 s79, s91, 0
	s_mov_b32 m0, s61
	s_nop 0
	global_load_lds_dwordx4 v132, s[78:79]
	s_mov_b32 m0, s62
	s_nop 0
	global_load_lds_dwordx4 v136, s[78:79]
	s_add_i32 s97, 0, 0x18000
	s_add_i32 s48, 0, 0x1c000
	ds_read_b128 v[150:153], v248
	ds_read_b128 v[154:157], v248 offset:1024
	ds_read_b128 v[158:161], v248 offset:2048
	ds_read_b128 v[162:165], v248 offset:3072
	ds_read_b128 v[166:169], v249
	ds_read_b128 v[170:173], v249 offset:1024
	ds_read_b128 v[174:177], v249 offset:2048
	ds_read_b128 v[178:181], v249 offset:3072
	ds_read_b128 v[182:185], v141 offset:32768
	ds_read_b128 v[186:189], v141 offset:33792
	ds_read_b128 v[190:193], v141 offset:34816
	ds_read_b128 v[194:197], v141 offset:35840
	ds_read_b128 v[198:201], v141 offset:36864
	ds_read_b128 v[202:205], v141 offset:37888
	ds_read_b128 v[210:213], v141 offset:38912
	ds_read_b128 v[214:217], v141 offset:39936
	s_waitcnt vmcnt(8)
	s_waitcnt lgkmcnt(0)
	s_setprio 1
	s_barrier
	v_mfma_f32_16x16x32_bf16 v[128:131], v[150:153], v[182:185], v[128:131]
	v_mfma_f32_16x16x32_bf16 v[124:127], v[158:161], v[182:185], v[124:127]
	v_mfma_f32_16x16x32_bf16 v[116:119], v[150:153], v[190:193], v[116:119]
	v_mfma_f32_16x16x32_bf16 v[108:111], v[158:161], v[190:193], v[108:111]
	v_mfma_f32_16x16x32_bf16 v[100:103], v[150:153], v[198:201], v[100:103]
	v_mfma_f32_16x16x32_bf16 v[92:95], v[158:161], v[198:201], v[92:95]
	v_mfma_f32_16x16x32_bf16 v[84:87], v[150:153], v[210:213], v[84:87]
	v_mfma_f32_16x16x32_bf16 v[76:79], v[158:161], v[210:213], v[76:79]
	v_mfma_f32_16x16x32_bf16 v[128:131], v[154:157], v[186:189], v[128:131]
	v_mfma_f32_16x16x32_bf16 v[124:127], v[162:165], v[186:189], v[124:127]
	v_mfma_f32_16x16x32_bf16 v[116:119], v[154:157], v[194:197], v[116:119]
	v_mfma_f32_16x16x32_bf16 v[108:111], v[162:165], v[194:197], v[108:111]
	v_mfma_f32_16x16x32_bf16 v[100:103], v[154:157], v[202:205], v[100:103]
	v_mfma_f32_16x16x32_bf16 v[92:95], v[162:165], v[202:205], v[92:95]
	v_mfma_f32_16x16x32_bf16 v[84:87], v[154:157], v[214:217], v[84:87]
	v_mfma_f32_16x16x32_bf16 v[76:79], v[162:165], v[214:217], v[76:79]
	v_mfma_f32_16x16x32_bf16 v[120:123], v[166:169], v[182:185], v[120:123]
	v_mfma_f32_16x16x32_bf16 v[112:115], v[174:177], v[182:185], v[112:115]
	v_mfma_f32_16x16x32_bf16 v[104:107], v[166:169], v[190:193], v[104:107]
	v_mfma_f32_16x16x32_bf16 v[96:99], v[174:177], v[190:193], v[96:99]
	v_mfma_f32_16x16x32_bf16 v[88:91], v[166:169], v[198:201], v[88:91]
	v_mfma_f32_16x16x32_bf16 v[80:83], v[174:177], v[198:201], v[80:83]
	v_mfma_f32_16x16x32_bf16 v[72:75], v[166:169], v[210:213], v[72:75]
	v_mfma_f32_16x16x32_bf16 v[68:71], v[174:177], v[210:213], v[68:71]
	v_mfma_f32_16x16x32_bf16 v[120:123], v[170:173], v[186:189], v[120:123]
	v_mfma_f32_16x16x32_bf16 v[112:115], v[178:181], v[186:189], v[112:115]
	v_mfma_f32_16x16x32_bf16 v[104:107], v[170:173], v[194:197], v[104:107]
	v_mfma_f32_16x16x32_bf16 v[96:99], v[178:181], v[194:197], v[96:99]
	v_mfma_f32_16x16x32_bf16 v[88:91], v[170:173], v[202:205], v[88:91]
	v_mfma_f32_16x16x32_bf16 v[80:83], v[178:181], v[202:205], v[80:83]
	v_mfma_f32_16x16x32_bf16 v[72:75], v[170:173], v[214:217], v[72:75]
	v_mfma_f32_16x16x32_bf16 v[68:71], v[178:181], v[214:217], v[68:71]
	s_barrier
	s_setprio 0
	s_add_i32 s77, s97, s29
	s_mov_b32 m0, s77
	s_nop 0
	s_add_u32 s98, s88, 0x80
	s_addc_u32 s99, s89, 0
	s_nop 0
	global_load_lds_dwordx4 v134, s[98:99]
	s_add_i32 m0, s77, 0x2000
	s_add_u32 s78, s88, 0x80080
	s_addc_u32 s79, s89, 0
	s_add_i32 s77, s48, s29
	global_load_lds_dwordx4 v138, s[98:99]
	s_mov_b32 m0, s77
	s_nop 0
	global_load_lds_dwordx4 v134, s[78:79]
	s_add_i32 m0, s77, 0x2000
	s_nop 0
	global_load_lds_dwordx4 v138, s[78:79]
	s_mov_b32 m0, s63
	s_nop 0
	s_add_u32 s98, s90, 0x80
	s_addc_u32 s99, s91, 0
	s_nop 0
	global_load_lds_dwordx4 v132, s[98:99]
	s_mov_b32 m0, s64
	s_nop 0
	global_load_lds_dwordx4 v136, s[98:99]
	ds_read_b128 v[182:185], v141 offset:49152
	ds_read_b128 v[186:189], v141 offset:50176
	ds_read_b128 v[190:193], v141 offset:51200
	ds_read_b128 v[194:197], v141 offset:52224
	ds_read_b128 v[198:201], v141 offset:53248
	ds_read_b128 v[202:205], v141 offset:54272
	ds_read_b128 v[210:213], v141 offset:55296
	ds_read_b128 v[214:217], v141 offset:56320
	s_waitcnt vmcnt(8)
	s_waitcnt lgkmcnt(0)
	s_setprio 1
	s_barrier
	v_mfma_f32_16x16x32_bf16 v[64:67], v[150:153], v[182:185], v[64:67]
	v_mfma_f32_16x16x32_bf16 v[60:63], v[158:161], v[182:185], v[60:63]
	v_mfma_f32_16x16x32_bf16 v[52:55], v[150:153], v[190:193], v[52:55]
	v_mfma_f32_16x16x32_bf16 v[44:47], v[158:161], v[190:193], v[44:47]
	v_mfma_f32_16x16x32_bf16 v[36:39], v[150:153], v[198:201], v[36:39]
	v_mfma_f32_16x16x32_bf16 v[28:31], v[158:161], v[198:201], v[28:31]
	v_mfma_f32_16x16x32_bf16 v[20:23], v[150:153], v[210:213], v[20:23]
	v_mfma_f32_16x16x32_bf16 v[12:15], v[158:161], v[210:213], v[12:15]
	v_mfma_f32_16x16x32_bf16 v[64:67], v[154:157], v[186:189], v[64:67]
	v_mfma_f32_16x16x32_bf16 v[60:63], v[162:165], v[186:189], v[60:63]
	v_mfma_f32_16x16x32_bf16 v[52:55], v[154:157], v[194:197], v[52:55]
	v_mfma_f32_16x16x32_bf16 v[44:47], v[162:165], v[194:197], v[44:47]
	v_mfma_f32_16x16x32_bf16 v[36:39], v[154:157], v[202:205], v[36:39]
	v_mfma_f32_16x16x32_bf16 v[28:31], v[162:165], v[202:205], v[28:31]
	v_mfma_f32_16x16x32_bf16 v[20:23], v[154:157], v[214:217], v[20:23]
	v_mfma_f32_16x16x32_bf16 v[12:15], v[162:165], v[214:217], v[12:15]
	v_mfma_f32_16x16x32_bf16 v[56:59], v[166:169], v[182:185], v[56:59]
	v_mfma_f32_16x16x32_bf16 v[48:51], v[174:177], v[182:185], v[48:51]
	v_mfma_f32_16x16x32_bf16 v[40:43], v[166:169], v[190:193], v[40:43]
	v_mfma_f32_16x16x32_bf16 v[32:35], v[174:177], v[190:193], v[32:35]
	v_mfma_f32_16x16x32_bf16 v[24:27], v[166:169], v[198:201], v[24:27]
	v_mfma_f32_16x16x32_bf16 v[16:19], v[174:177], v[198:201], v[16:19]
	v_mfma_f32_16x16x32_bf16 v[8:11], v[166:169], v[210:213], v[8:11]
	v_mfma_f32_16x16x32_bf16 v[4:7], v[174:177], v[210:213], v[4:7]
	v_mfma_f32_16x16x32_bf16 v[56:59], v[170:173], v[186:189], v[56:59]
	v_mfma_f32_16x16x32_bf16 v[48:51], v[178:181], v[186:189], v[48:51]
	v_mfma_f32_16x16x32_bf16 v[40:43], v[170:173], v[194:197], v[40:43]
	v_mfma_f32_16x16x32_bf16 v[32:35], v[178:181], v[194:197], v[32:35]
	v_mfma_f32_16x16x32_bf16 v[24:27], v[170:173], v[202:205], v[24:27]
	v_mfma_f32_16x16x32_bf16 v[16:19], v[178:181], v[202:205], v[16:19]
	v_mfma_f32_16x16x32_bf16 v[8:11], v[170:173], v[214:217], v[8:11]
	v_mfma_f32_16x16x32_bf16 v[4:7], v[178:181], v[214:217], v[4:7]
	s_barrier
	s_setprio 0
	s_add_u32 s0, s0, 0x100
	s_addc_u32 s1, s1, 0
	s_add_u32 s56, s56, 0x100
	s_addc_u32 s57, s57, 0
	s_cmp_ge_i32 s76, s55
	s_mov_b32 s88, s76
	s_cbranch_scc0 .LBB0_246
	s_and_b64 vcc, exec, s[58:59]
	s_cbranch_vccz .LBB0_249
	s_barrier

.LBB0_283:
	s_or_b64 exec, exec, s[88:89]
	s_cmp_eq_u32 s13, 2
	s_mov_b64 s[0:1], -1
	s_cbranch_scc1 .LBB0_237
	s_andn2_b64 vcc, exec, s[36:37]
	s_cbranch_vccnz .LBB0_236
	s_mov_b32 s100, 1
	s_branch .LBB0_236

.LBB0_520:
	s_add_i32 s9, s64, -2
	s_add_u32 s74, s74, 0x80080
	s_addc_u32 s75, s75, 0
	s_add_u32 s23, s84, 0x100
	s_addc_u32 s35, s85, 0
	s_mov_b32 s54, 0
	v_mov_b64_e32 v[4:5], 0
	v_mov_b64_e32 v[6:7], 0
	v_mov_b64_e32 v[8:9], 0
	v_mov_b64_e32 v[10:11], 0
	v_mov_b64_e32 v[12:13], 0
	v_mov_b64_e32 v[14:15], 0
	v_mov_b64_e32 v[16:17], 0
	v_mov_b64_e32 v[18:19], 0
	v_mov_b64_e32 v[20:21], 0
	v_mov_b64_e32 v[22:23], 0
	v_mov_b64_e32 v[24:25], 0
	v_mov_b64_e32 v[26:27], 0
	v_mov_b64_e32 v[28:29], 0
	v_mov_b64_e32 v[30:31], 0
	v_mov_b64_e32 v[32:33], 0
	v_mov_b64_e32 v[34:35], 0
	v_mov_b64_e32 v[36:37], 0
	v_mov_b64_e32 v[38:39], 0
	v_mov_b64_e32 v[40:41], 0
	v_mov_b64_e32 v[42:43], 0
	v_mov_b64_e32 v[44:45], 0
	v_mov_b64_e32 v[46:47], 0
	v_mov_b64_e32 v[48:49], 0
	v_mov_b64_e32 v[50:51], 0
	v_mov_b64_e32 v[52:53], 0
	v_mov_b64_e32 v[54:55], 0
	v_mov_b64_e32 v[56:57], 0
	v_mov_b64_e32 v[58:59], 0
	v_mov_b64_e32 v[60:61], 0
	v_mov_b64_e32 v[62:63], 0
	v_mov_b64_e32 v[64:65], 0
	v_mov_b64_e32 v[66:67], 0
	v_mov_b64_e32 v[68:69], 0
	v_mov_b64_e32 v[70:71], 0
	v_mov_b64_e32 v[72:73], 0
	v_mov_b64_e32 v[74:75], 0
	v_mov_b64_e32 v[76:77], 0
	v_mov_b64_e32 v[78:79], 0
	v_mov_b64_e32 v[80:81], 0
	v_mov_b64_e32 v[82:83], 0
	v_mov_b64_e32 v[84:85], 0
	v_mov_b64_e32 v[86:87], 0
	v_mov_b64_e32 v[88:89], 0
	v_mov_b64_e32 v[90:91], 0
	v_mov_b64_e32 v[92:93], 0
	v_mov_b64_e32 v[94:95], 0
	v_mov_b64_e32 v[96:97], 0
	v_mov_b64_e32 v[98:99], 0
	v_mov_b64_e32 v[100:101], 0
	v_mov_b64_e32 v[102:103], 0
	v_mov_b64_e32 v[104:105], 0
	v_mov_b64_e32 v[106:107], 0
	v_mov_b64_e32 v[108:109], 0
	v_mov_b64_e32 v[110:111], 0
	v_mov_b64_e32 v[112:113], 0
	v_mov_b64_e32 v[114:115], 0
	v_mov_b64_e32 v[116:117], 0
	v_mov_b64_e32 v[118:119], 0
	v_mov_b64_e32 v[120:121], 0
	v_mov_b64_e32 v[122:123], 0
	v_mov_b64_e32 v[124:125], 0
	v_mov_b64_e32 v[126:127], 0
	v_mov_b64_e32 v[128:129], 0
	v_mov_b64_e32 v[130:131], 0
	v_add_u32_e32 v246, 0x10000, v142
	v_add_u32_e32 v247, 0x14000, v142
	v_add_u32_e32 v248, 0x18000, v142
	v_add_u32_e32 v249, 0x1c000, v142
	s_cmp_eq_u32 s100, 0
	s_cbranch_scc1 .Lrs3
	s_barrier
	s_mov_b32 s100, 0
.Lrs3:
.LBB0_521:
	s_add_i32 s55, s54, 2
	s_add_u32 s56, s74, 0xfff80080
	s_addc_u32 s57, s75, -1
	s_add_i32 m0, s17, 0xc000
	s_add_i32 s76, s17, 0xe000
	global_load_lds_dwordx4 v138, s[74:75]
	s_mov_b32 m0, s76
	s_cmp_eq_u32 s9, s54
	global_load_lds_dwordx4 v140, s[74:75]
	s_cselect_b32 s87, s69, s57
	s_cselect_b32 s86, s68, s56
	s_cselect_b32 s85, s73, s35
	s_cselect_b32 s84, s72, s23
	ds_read_b128 v[146:149], v246
	ds_read_b128 v[150:153], v246 offset:1024
	ds_read_b128 v[154:157], v246 offset:2048
	ds_read_b128 v[158:161], v246 offset:3072
	ds_read_b128 v[162:165], v247
	ds_read_b128 v[166:169], v247 offset:1024
	ds_read_b128 v[170:173], v247 offset:2048
	ds_read_b128 v[174:177], v247 offset:3072
	ds_read_b128 v[178:181], v144
	ds_read_b128 v[182:185], v144 offset:1024
	ds_read_b128 v[186:189], v144 offset:2048
	ds_read_b128 v[190:193], v144 offset:3072
	ds_read_b128 v[194:197], v144 offset:4096
	ds_read_b128 v[198:201], v144 offset:5120
	ds_read_b128 v[202:205], v144 offset:6144
	ds_read_b128 v[210:213], v144 offset:7168
	s_waitcnt vmcnt(8)
	s_waitcnt lgkmcnt(0)
	s_setprio 1
	s_barrier
	v_mfma_f32_16x16x32_bf16 v[128:131], v[146:149], v[178:181], v[128:131]
	v_mfma_f32_16x16x32_bf16 v[124:127], v[154:157], v[178:181], v[124:127]
	v_mfma_f32_16x16x32_bf16 v[120:123], v[146:149], v[186:189], v[120:123]
	v_mfma_f32_16x16x32_bf16 v[116:119], v[154:157], v[186:189], v[116:119]
	v_mfma_f32_16x16x32_bf16 v[104:107], v[146:149], v[194:197], v[104:107]
	v_mfma_f32_16x16x32_bf16 v[100:103], v[154:157], v[194:197], v[100:103]
	v_mfma_f32_16x16x32_bf16 v[88:91], v[146:149], v[202:205], v[88:91]
	v_mfma_f32_16x16x32_bf16 v[84:87], v[154:157], v[202:205], v[84:87]
	v_mfma_f32_16x16x32_bf16 v[128:131], v[150:153], v[182:185], v[128:131]
	v_mfma_f32_16x16x32_bf16 v[124:127], v[158:161], v[182:185], v[124:127]
	v_mfma_f32_16x16x32_bf16 v[120:123], v[150:153], v[190:193], v[120:123]
	v_mfma_f32_16x16x32_bf16 v[116:119], v[158:161], v[190:193], v[116:119]
	v_mfma_f32_16x16x32_bf16 v[104:107], v[150:153], v[198:201], v[104:107]
	v_mfma_f32_16x16x32_bf16 v[100:103], v[158:161], v[198:201], v[100:103]
	v_mfma_f32_16x16x32_bf16 v[88:91], v[150:153], v[210:213], v[88:91]
	v_mfma_f32_16x16x32_bf16 v[84:87], v[158:161], v[210:213], v[84:87]
	v_mfma_f32_16x16x32_bf16 v[112:115], v[162:165], v[178:181], v[112:115]
	v_mfma_f32_16x16x32_bf16 v[108:111], v[170:173], v[178:181], v[108:111]
	v_mfma_f32_16x16x32_bf16 v[96:99], v[162:165], v[186:189], v[96:99]
	v_mfma_f32_16x16x32_bf16 v[92:95], v[170:173], v[186:189], v[92:95]
	v_mfma_f32_16x16x32_bf16 v[80:83], v[162:165], v[194:197], v[80:83]
	v_mfma_f32_16x16x32_bf16 v[76:79], v[170:173], v[194:197], v[76:79]
	v_mfma_f32_16x16x32_bf16 v[72:75], v[162:165], v[202:205], v[72:75]
	v_mfma_f32_16x16x32_bf16 v[68:71], v[170:173], v[202:205], v[68:71]
	v_mfma_f32_16x16x32_bf16 v[112:115], v[166:169], v[182:185], v[112:115]
	v_mfma_f32_16x16x32_bf16 v[108:111], v[174:177], v[182:185], v[108:111]
	v_mfma_f32_16x16x32_bf16 v[96:99], v[166:169], v[190:193], v[96:99]
	v_mfma_f32_16x16x32_bf16 v[92:95], v[174:177], v[190:193], v[92:95]
	v_mfma_f32_16x16x32_bf16 v[80:83], v[166:169], v[198:201], v[80:83]
	v_mfma_f32_16x16x32_bf16 v[76:79], v[174:177], v[198:201], v[76:79]
	v_mfma_f32_16x16x32_bf16 v[72:75], v[166:169], v[210:213], v[72:75]
	v_mfma_f32_16x16x32_bf16 v[68:71], v[174:177], v[210:213], v[68:71]
	s_barrier
	s_setprio 0
	s_add_i32 s54, s33, s16
	s_mov_b32 m0, s54
	s_nop 0
	global_load_lds_dwordx4 v2, s[84:85]
	s_add_i32 m0, s54, 0x2000
	s_add_u32 s56, s84, 0x80000
	s_addc_u32 s57, s85, 0
	s_add_i32 s54, s96, s16
	global_load_lds_dwordx4 v136, s[84:85]
	s_mov_b32 m0, s54
	s_nop 0
	global_load_lds_dwordx4 v2, s[56:57]
	s_add_i32 m0, s54, 0x2000
	s_nop 0
	global_load_lds_dwordx4 v136, s[56:57]
	s_mov_b32 m0, s17
	s_nop 0
	global_load_lds_dwordx4 v132, s[86:87]
	s_mov_b32 m0, s29
	s_nop 0
	global_load_lds_dwordx4 v134, s[86:87]
	ds_read_b128 v[178:181], v144 offset:16384
	ds_read_b128 v[182:185], v144 offset:17408
	ds_read_b128 v[186:189], v144 offset:18432
	ds_read_b128 v[190:193], v144 offset:19456
	ds_read_b128 v[194:197], v144 offset:20480
	ds_read_b128 v[198:201], v144 offset:21504
	ds_read_b128 v[202:205], v144 offset:22528
	ds_read_b128 v[210:213], v144 offset:23552
	s_waitcnt vmcnt(8)
	s_waitcnt lgkmcnt(0)
	s_setprio 1
	s_barrier
	v_mfma_f32_16x16x32_bf16 v[64:67], v[146:149], v[178:181], v[64:67]
	v_mfma_f32_16x16x32_bf16 v[60:63], v[154:157], v[178:181], v[60:63]
	v_mfma_f32_16x16x32_bf16 v[56:59], v[146:149], v[186:189], v[56:59]
	v_mfma_f32_16x16x32_bf16 v[52:55], v[154:157], v[186:189], v[52:55]
	v_mfma_f32_16x16x32_bf16 v[40:43], v[146:149], v[194:197], v[40:43]
	v_mfma_f32_16x16x32_bf16 v[36:39], v[154:157], v[194:197], v[36:39]
	v_mfma_f32_16x16x32_bf16 v[24:27], v[146:149], v[202:205], v[24:27]
	v_mfma_f32_16x16x32_bf16 v[20:23], v[154:157], v[202:205], v[20:23]
	v_mfma_f32_16x16x32_bf16 v[64:67], v[150:153], v[182:185], v[64:67]
	v_mfma_f32_16x16x32_bf16 v[60:63], v[158:161], v[182:185], v[60:63]
	v_mfma_f32_16x16x32_bf16 v[56:59], v[150:153], v[190:193], v[56:59]
	v_mfma_f32_16x16x32_bf16 v[52:55], v[158:161], v[190:193], v[52:55]
	v_mfma_f32_16x16x32_bf16 v[40:43], v[150:153], v[198:201], v[40:43]
	v_mfma_f32_16x16x32_bf16 v[36:39], v[158:161], v[198:201], v[36:39]
	v_mfma_f32_16x16x32_bf16 v[24:27], v[150:153], v[210:213], v[24:27]
	v_mfma_f32_16x16x32_bf16 v[20:23], v[158:161], v[210:213], v[20:23]
	v_mfma_f32_16x16x32_bf16 v[48:51], v[162:165], v[178:181], v[48:51]
	v_mfma_f32_16x16x32_bf16 v[44:47], v[170:173], v[178:181], v[44:47]
	v_mfma_f32_16x16x32_bf16 v[32:35], v[162:165], v[186:189], v[32:35]
	v_mfma_f32_16x16x32_bf16 v[28:31], v[170:173], v[186:189], v[28:31]
	v_mfma_f32_16x16x32_bf16 v[16:19], v[162:165], v[194:197], v[16:19]
	v_mfma_f32_16x16x32_bf16 v[12:15], v[170:173], v[194:197], v[12:15]
	v_mfma_f32_16x16x32_bf16 v[8:11], v[162:165], v[202:205], v[8:11]
	v_mfma_f32_16x16x32_bf16 v[4:7], v[170:173], v[202:205], v[4:7]
	v_mfma_f32_16x16x32_bf16 v[48:51], v[166:169], v[182:185], v[48:51]
	v_mfma_f32_16x16x32_bf16 v[44:47], v[174:177], v[182:185], v[44:47]
	v_mfma_f32_16x16x32_bf16 v[32:35], v[166:169], v[190:193], v[32:35]
	v_mfma_f32_16x16x32_bf16 v[28:31], v[174:177], v[190:193], v[28:31]
	v_mfma_f32_16x16x32_bf16 v[16:19], v[166:169], v[198:201], v[16:19]
	v_mfma_f32_16x16x32_bf16 v[12:15], v[174:177], v[198:201], v[12:15]
	v_mfma_f32_16x16x32_bf16 v[8:11], v[166:169], v[210:213], v[8:11]
	v_mfma_f32_16x16x32_bf16 v[4:7], v[174:177], v[210:213], v[4:7]
	s_barrier
	s_setprio 0
	s_add_u32 s56, s86, 0x80000
	s_addc_u32 s57, s87, 0
	s_mov_b32 m0, s60
	s_nop 0
	global_load_lds_dwordx4 v132, s[56:57]
	s_mov_b32 m0, s61
	s_nop 0
	global_load_lds_dwordx4 v134, s[56:57]
	ds_read_b128 v[146:149], v248
	ds_read_b128 v[150:153], v248 offset:1024
	ds_read_b128 v[154:157], v248 offset:2048
	ds_read_b128 v[158:161], v248 offset:3072
	ds_read_b128 v[162:165], v249
	ds_read_b128 v[166:169], v249 offset:1024
	ds_read_b128 v[170:173], v249 offset:2048
	ds_read_b128 v[174:177], v249 offset:3072
	ds_read_b128 v[178:181], v144 offset:32768
	ds_read_b128 v[182:185], v144 offset:33792
	ds_read_b128 v[186:189], v144 offset:34816
	ds_read_b128 v[190:193], v144 offset:35840
	ds_read_b128 v[194:197], v144 offset:36864
	ds_read_b128 v[198:201], v144 offset:37888
	ds_read_b128 v[202:205], v144 offset:38912
	ds_read_b128 v[210:213], v144 offset:39936
	s_waitcnt vmcnt(8)
	s_waitcnt lgkmcnt(0)
	s_setprio 1
	s_barrier
	v_mfma_f32_16x16x32_bf16 v[128:131], v[146:149], v[178:181], v[128:131]
	v_mfma_f32_16x16x32_bf16 v[124:127], v[154:157], v[178:181], v[124:127]
	v_mfma_f32_16x16x32_bf16 v[120:123], v[146:149], v[186:189], v[120:123]
	v_mfma_f32_16x16x32_bf16 v[116:119], v[154:157], v[186:189], v[116:119]
	v_mfma_f32_16x16x32_bf16 v[104:107], v[146:149], v[194:197], v[104:107]
	v_mfma_f32_16x16x32_bf16 v[100:103], v[154:157], v[194:197], v[100:103]
	v_mfma_f32_16x16x32_bf16 v[88:91], v[146:149], v[202:205], v[88:91]
	v_mfma_f32_16x16x32_bf16 v[84:87], v[154:157], v[202:205], v[84:87]
	v_mfma_f32_16x16x32_bf16 v[128:131], v[150:153], v[182:185], v[128:131]
	v_mfma_f32_16x16x32_bf16 v[124:127], v[158:161], v[182:185], v[124:127]
	v_mfma_f32_16x16x32_bf16 v[120:123], v[150:153], v[190:193], v[120:123]
	v_mfma_f32_16x16x32_bf16 v[116:119], v[158:161], v[190:193], v[116:119]
	v_mfma_f32_16x16x32_bf16 v[104:107], v[150:153], v[198:201], v[104:107]
	v_mfma_f32_16x16x32_bf16 v[100:103], v[158:161], v[198:201], v[100:103]
	v_mfma_f32_16x16x32_bf16 v[88:91], v[150:153], v[210:213], v[88:91]
	v_mfma_f32_16x16x32_bf16 v[84:87], v[158:161], v[210:213], v[84:87]
	v_mfma_f32_16x16x32_bf16 v[112:115], v[162:165], v[178:181], v[112:115]
	v_mfma_f32_16x16x32_bf16 v[108:111], v[170:173], v[178:181], v[108:111]
	v_mfma_f32_16x16x32_bf16 v[96:99], v[162:165], v[186:189], v[96:99]
	v_mfma_f32_16x16x32_bf16 v[92:95], v[170:173], v[186:189], v[92:95]
	v_mfma_f32_16x16x32_bf16 v[80:83], v[162:165], v[194:197], v[80:83]
	v_mfma_f32_16x16x32_bf16 v[76:79], v[170:173], v[194:197], v[76:79]
	v_mfma_f32_16x16x32_bf16 v[72:75], v[162:165], v[202:205], v[72:75]
	v_mfma_f32_16x16x32_bf16 v[68:71], v[170:173], v[202:205], v[68:71]
	v_mfma_f32_16x16x32_bf16 v[112:115], v[166:169], v[182:185], v[112:115]
	v_mfma_f32_16x16x32_bf16 v[108:111], v[174:177], v[182:185], v[108:111]
	v_mfma_f32_16x16x32_bf16 v[96:99], v[166:169], v[190:193], v[96:99]
	v_mfma_f32_16x16x32_bf16 v[92:95], v[174:177], v[190:193], v[92:95]
	v_mfma_f32_16x16x32_bf16 v[80:83], v[166:169], v[198:201], v[80:83]
	v_mfma_f32_16x16x32_bf16 v[76:79], v[174:177], v[198:201], v[76:79]
	v_mfma_f32_16x16x32_bf16 v[72:75], v[166:169], v[210:213], v[72:75]
	v_mfma_f32_16x16x32_bf16 v[68:71], v[174:177], v[210:213], v[68:71]
	s_barrier
	s_setprio 0
	s_add_i32 s54, s97, s16
	s_mov_b32 m0, s54
	s_nop 0
	s_add_u32 s98, s84, 0x80
	s_addc_u32 s99, s85, 0
	s_nop 0
	global_load_lds_dwordx4 v2, s[98:99]
	s_add_i32 m0, s54, 0x2000
	s_add_u32 s56, s84, 0x80080
	s_addc_u32 s57, s85, 0
	s_add_i32 s54, s48, s16
	global_load_lds_dwordx4 v136, s[98:99]
	s_mov_b32 m0, s54
	s_nop 0
	global_load_lds_dwordx4 v2, s[56:57]
	s_add_i32 m0, s54, 0x2000
	s_nop 0
	global_load_lds_dwordx4 v136, s[56:57]
	s_mov_b32 m0, s62
	s_nop 0
	s_add_u32 s98, s86, 0x80
	s_addc_u32 s99, s87, 0
	s_nop 0
	global_load_lds_dwordx4 v132, s[98:99]
	s_mov_b32 m0, s63
	s_nop 0
	global_load_lds_dwordx4 v134, s[98:99]
	ds_read_b128 v[178:181], v144 offset:49152
	ds_read_b128 v[182:185], v144 offset:50176
	ds_read_b128 v[186:189], v144 offset:51200
	ds_read_b128 v[190:193], v144 offset:52224
	ds_read_b128 v[194:197], v144 offset:53248
	ds_read_b128 v[198:201], v144 offset:54272
	ds_read_b128 v[202:205], v144 offset:55296
	ds_read_b128 v[210:213], v144 offset:56320
	s_waitcnt vmcnt(8)
	s_waitcnt lgkmcnt(0)
	s_setprio 1
	s_barrier
	v_mfma_f32_16x16x32_bf16 v[64:67], v[146:149], v[178:181], v[64:67]
	v_mfma_f32_16x16x32_bf16 v[60:63], v[154:157], v[178:181], v[60:63]
	v_mfma_f32_16x16x32_bf16 v[56:59], v[146:149], v[186:189], v[56:59]
	v_mfma_f32_16x16x32_bf16 v[52:55], v[154:157], v[186:189], v[52:55]
	v_mfma_f32_16x16x32_bf16 v[40:43], v[146:149], v[194:197], v[40:43]
	v_mfma_f32_16x16x32_bf16 v[36:39], v[154:157], v[194:197], v[36:39]
	v_mfma_f32_16x16x32_bf16 v[24:27], v[146:149], v[202:205], v[24:27]
	v_mfma_f32_16x16x32_bf16 v[20:23], v[154:157], v[202:205], v[20:23]
	v_mfma_f32_16x16x32_bf16 v[64:67], v[150:153], v[182:185], v[64:67]
	v_mfma_f32_16x16x32_bf16 v[60:63], v[158:161], v[182:185], v[60:63]
	v_mfma_f32_16x16x32_bf16 v[56:59], v[150:153], v[190:193], v[56:59]
	v_mfma_f32_16x16x32_bf16 v[52:55], v[158:161], v[190:193], v[52:55]
	v_mfma_f32_16x16x32_bf16 v[40:43], v[150:153], v[198:201], v[40:43]
	v_mfma_f32_16x16x32_bf16 v[36:39], v[158:161], v[198:201], v[36:39]
	v_mfma_f32_16x16x32_bf16 v[24:27], v[150:153], v[210:213], v[24:27]
	v_mfma_f32_16x16x32_bf16 v[20:23], v[158:161], v[210:213], v[20:23]
	v_mfma_f32_16x16x32_bf16 v[48:51], v[162:165], v[178:181], v[48:51]
	v_mfma_f32_16x16x32_bf16 v[44:47], v[170:173], v[178:181], v[44:47]
	v_mfma_f32_16x16x32_bf16 v[32:35], v[162:165], v[186:189], v[32:35]
	v_mfma_f32_16x16x32_bf16 v[28:31], v[170:173], v[186:189], v[28:31]
	v_mfma_f32_16x16x32_bf16 v[16:19], v[162:165], v[194:197], v[16:19]
	v_mfma_f32_16x16x32_bf16 v[12:15], v[170:173], v[194:197], v[12:15]
	v_mfma_f32_16x16x32_bf16 v[8:11], v[162:165], v[202:205], v[8:11]
	v_mfma_f32_16x16x32_bf16 v[4:7], v[170:173], v[202:205], v[4:7]
	v_mfma_f32_16x16x32_bf16 v[48:51], v[166:169], v[182:185], v[48:51]
	v_mfma_f32_16x16x32_bf16 v[44:47], v[174:177], v[182:185], v[44:47]
	v_mfma_f32_16x16x32_bf16 v[32:35], v[166:169], v[190:193], v[32:35]
	v_mfma_f32_16x16x32_bf16 v[28:31], v[174:177], v[190:193], v[28:31]
	v_mfma_f32_16x16x32_bf16 v[16:19], v[166:169], v[198:201], v[16:19]
	v_mfma_f32_16x16x32_bf16 v[12:15], v[174:177], v[198:201], v[12:15]
	v_mfma_f32_16x16x32_bf16 v[8:11], v[166:169], v[210:213], v[8:11]
	v_mfma_f32_16x16x32_bf16 v[4:7], v[174:177], v[210:213], v[4:7]
	s_barrier
	s_setprio 0
	s_add_u32 s74, s74, 0x100
	s_addc_u32 s75, s75, 0
	s_add_u32 s23, s23, 0x100
	s_addc_u32 s35, s35, 0
	s_cmp_ge_u32 s55, s64
	s_mov_b32 s54, s55
	s_cbranch_scc0 .LBB0_521
	s_and_b64 vcc, exec, s[58:59]
	s_cbranch_vccz .LBB0_524
	s_barrier
.LBB0_524:
	s_lshl_b32 s9, s51, 8
	s_add_i32 s23, s9, 0xffffe000
	s_cmp_eq_u32 s50, 0
	s_cselect_b32 s9, s9, s23
	s_mov_b32 s23, 0x21c00000
	s_cselect_b32 s23, s23, 0x33c00000
	s_add_u32 s50, s94, s23
	v_lshl_or_b32 v146, s22, 8, v143
	v_add_u32_e32 v148, s9, v1
	s_addc_u32 s51, s95, 0
	v_ashrrev_i32_e32 v147, 31, v146
	v_ashrrev_i32_e32 v149, 31, v148
	v_lshl_add_u64 v[146:147], v[146:147], 1, s[50:51]
	v_lshlrev_b64 v[150:151], 12, v[148:149]
	v_lshl_add_u64 v[150:151], v[146:147], 0, v[150:151]
	s_mov_b32 s9, 0x80000
	s_mov_b64 s[50:51], 0x80000
	v_cvt_pk_bf16_f32 v64, v64, v65
	v_cvt_pk_bf16_f32 v65, v66, v67
	v_cvt_pk_bf16_f32 v66, v60, v61
	v_add_co_u32_e32 v60, vcc, s9, v150
	v_cvt_pk_bf16_f32 v72, v72, v73
	v_cvt_pk_bf16_f32 v73, v74, v75
	v_cvt_pk_bf16_f32 v74, v68, v69
	v_lshl_add_u64 v[68:69], v[150:151], 0, s[50:51]
	v_addc_co_u32_e32 v61, vcc, 0, v151, vcc
	v_cvt_pk_bf16_f32 v48, v48, v49
	v_cvt_pk_bf16_f32 v49, v50, v51
	v_cvt_pk_bf16_f32 v50, v44, v45
	v_cvt_pk_bf16_f32 v51, v46, v47
	s_mov_b32 s9, 0x90000
	ds_bpermute_b32 v222, v231, v48
	ds_bpermute_b32 v223, v231, v49
	ds_bpermute_b32 v224, v231, v50
	ds_bpermute_b32 v225, v231, v51
	s_mov_b64 s[50:51], 0x90000
	v_cvt_pk_bf16_f32 v112, v112, v113
	v_add_co_u32_e32 v50, vcc, s9, v150
	v_cvt_pk_bf16_f32 v113, v114, v115
	v_cvt_pk_bf16_f32 v114, v108, v109
	v_or_b32_e32 v108, 16, v148
	v_lshl_add_u64 v[48:49], v[150:151], 0, s[50:51]
	v_addc_co_u32_e32 v51, vcc, 0, v151, vcc
	v_cvt_pk_bf16_f32 v32, v32, v33
	v_cvt_pk_bf16_f32 v33, v34, v35
	v_cvt_pk_bf16_f32 v34, v28, v29
	v_cvt_pk_bf16_f32 v35, v30, v31
	s_mov_b32 s9, 0xa0000
	v_ashrrev_i32_e32 v109, 31, v108
	v_cvt_pk_bf16_f32 v96, v96, v97
	v_cvt_pk_bf16_f32 v97, v98, v99
	v_cvt_pk_bf16_f32 v98, v92, v93
	v_or_b32_e32 v92, 32, v148
	s_waitcnt lgkmcnt(0)
	global_store_dwordx4 v[68:69], v[222:225], off offset:256
	ds_bpermute_b32 v226, v231, v32
	ds_bpermute_b32 v227, v231, v33
	ds_bpermute_b32 v228, v231, v34
	ds_bpermute_b32 v229, v231, v35
	s_mov_b64 s[50:51], 0xa0000
	v_cvt_pk_bf16_f32 v115, v110, v111
	v_add_co_u32_e32 v34, vcc, s9, v150
	v_lshlrev_b64 v[108:109], 12, v[108:109]
	v_ashrrev_i32_e32 v93, 31, v92
	v_cvt_pk_bf16_f32 v80, v80, v81
	v_cvt_pk_bf16_f32 v81, v82, v83
	v_cvt_pk_bf16_f32 v82, v76, v77
	v_or_b32_e32 v76, 48, v148
	v_lshl_add_u64 v[32:33], v[150:151], 0, s[50:51]
	v_addc_co_u32_e32 v35, vcc, 0, v151, vcc
	v_cvt_pk_bf16_f32 v16, v16, v17
	v_cvt_pk_bf16_f32 v17, v18, v19
	v_cvt_pk_bf16_f32 v18, v12, v13
	v_cvt_pk_bf16_f32 v19, v14, v15
	s_mov_b32 s9, 0xb0000
	s_waitcnt lgkmcnt(0)
	global_store_dwordx4 v[48:49], v[226:229], off offset:256
	ds_bpermute_b32 v222, v231, v112
	ds_bpermute_b32 v223, v231, v113
	ds_bpermute_b32 v224, v231, v114
	ds_bpermute_b32 v225, v231, v115
	v_cvt_pk_bf16_f32 v99, v94, v95
	v_lshlrev_b64 v[92:93], 12, v[92:93]
	v_lshl_add_u64 v[112:113], v[146:147], 0, v[108:109]
	v_ashrrev_i32_e32 v77, 31, v76
	s_waitcnt lgkmcnt(0)
	global_store_dwordx4 v[150:151], v[222:225], off offset:256
	ds_bpermute_b32 v226, v231, v16
	ds_bpermute_b32 v227, v231, v17
	ds_bpermute_b32 v228, v231, v18
	ds_bpermute_b32 v229, v231, v19
	s_waitcnt lgkmcnt(0)
	global_store_dwordx4 v[32:33], v[226:229], off offset:256
	ds_bpermute_b32 v222, v231, v96
	ds_bpermute_b32 v223, v231, v97
	ds_bpermute_b32 v224, v231, v98
	ds_bpermute_b32 v225, v231, v99
	v_cvt_pk_bf16_f32 v83, v78, v79
	v_add_co_u32_e32 v18, vcc, s9, v150
	v_lshl_add_u64 v[96:97], v[146:147], 0, v[92:93]
	v_lshlrev_b64 v[76:77], 12, v[76:77]
	s_mov_b64 s[50:51], 0xb0000
	v_addc_co_u32_e32 v19, vcc, 0, v151, vcc
	v_cvt_pk_bf16_f32 v128, v128, v129
	v_cvt_pk_bf16_f32 v129, v130, v131
	v_cvt_pk_bf16_f32 v130, v124, v125
	v_cvt_pk_bf16_f32 v131, v126, v127
	v_cvt_pk_bf16_f32 v108, v120, v121
	v_cvt_pk_bf16_f32 v109, v122, v123
	v_cvt_pk_bf16_f32 v110, v116, v117
	v_cvt_pk_bf16_f32 v111, v118, v119
	v_cvt_pk_bf16_f32 v92, v104, v105
	v_cvt_pk_bf16_f32 v93, v106, v107
	v_cvt_pk_bf16_f32 v94, v100, v101
	v_cvt_pk_bf16_f32 v95, v102, v103
	s_waitcnt lgkmcnt(0)
	global_store_dwordx4 v[112:113], v[222:225], off offset:256
	ds_bpermute_b32 v226, v231, v80
	ds_bpermute_b32 v227, v231, v81
	ds_bpermute_b32 v228, v231, v82
	ds_bpermute_b32 v229, v231, v83
	v_cvt_pk_bf16_f32 v78, v84, v85
	v_cvt_pk_bf16_f32 v79, v86, v87
	v_lshl_add_u64 v[80:81], v[146:147], 0, v[76:77]
	v_cvt_pk_bf16_f32 v76, v88, v89
	v_cvt_pk_bf16_f32 v77, v90, v91
	v_cvt_pk_bf16_f32 v75, v70, v71
	v_cvt_pk_bf16_f32 v67, v62, v63
	v_cvt_pk_bf16_f32 v44, v56, v57
	v_cvt_pk_bf16_f32 v45, v58, v59
	v_cvt_pk_bf16_f32 v46, v52, v53
	v_cvt_pk_bf16_f32 v47, v54, v55
	v_cvt_pk_bf16_f32 v28, v40, v41
	v_cvt_pk_bf16_f32 v29, v42, v43
	v_cvt_pk_bf16_f32 v30, v36, v37
	v_cvt_pk_bf16_f32 v31, v38, v39
	v_lshl_add_u64 v[16:17], v[150:151], 0, s[50:51]
	v_cvt_pk_bf16_f32 v12, v24, v25
	v_cvt_pk_bf16_f32 v13, v26, v27
	v_cvt_pk_bf16_f32 v14, v20, v21
	v_cvt_pk_bf16_f32 v15, v22, v23
	v_cvt_pk_bf16_f32 v8, v8, v9
	v_cvt_pk_bf16_f32 v9, v10, v11
	v_cvt_pk_bf16_f32 v10, v4, v5
	v_cvt_pk_bf16_f32 v11, v6, v7
	s_and_b64 vcc, exec, s[0:1]
	s_mov_b64 s[0:1], -1
	s_waitcnt lgkmcnt(0)
	global_store_dwordx4 v[96:97], v[226:229], off offset:256
	ds_bpermute_b32 v222, v231, v128
	ds_bpermute_b32 v223, v231, v129
	ds_bpermute_b32 v224, v231, v130
	ds_bpermute_b32 v225, v231, v131
	s_waitcnt lgkmcnt(0)
	global_store_dwordx4 v[150:151], v[222:225], off
	ds_bpermute_b32 v226, v231, v108
	ds_bpermute_b32 v227, v231, v109
	ds_bpermute_b32 v228, v231, v110
	ds_bpermute_b32 v229, v231, v111
	s_waitcnt lgkmcnt(0)
	global_store_dwordx4 v[112:113], v[226:229], off
	ds_bpermute_b32 v222, v231, v92
	ds_bpermute_b32 v223, v231, v93
	ds_bpermute_b32 v224, v231, v94
	ds_bpermute_b32 v225, v231, v95
	s_waitcnt lgkmcnt(0)
	global_store_dwordx4 v[96:97], v[222:225], off
	ds_bpermute_b32 v226, v231, v76
	ds_bpermute_b32 v227, v231, v77
	ds_bpermute_b32 v228, v231, v78
	ds_bpermute_b32 v229, v231, v79
	s_waitcnt lgkmcnt(0)
	global_store_dwordx4 v[80:81], v[226:229], off
	ds_bpermute_b32 v222, v231, v72
	ds_bpermute_b32 v223, v231, v73
	ds_bpermute_b32 v224, v231, v74
	ds_bpermute_b32 v225, v231, v75
	s_waitcnt lgkmcnt(0)
	global_store_dwordx4 v[80:81], v[222:225], off offset:256
	ds_bpermute_b32 v226, v231, v64
	ds_bpermute_b32 v227, v231, v65
	ds_bpermute_b32 v228, v231, v66
	ds_bpermute_b32 v229, v231, v67
	s_waitcnt lgkmcnt(0)
	global_store_dwordx4 v[60:61], v[226:229], off
	ds_bpermute_b32 v222, v231, v44
	ds_bpermute_b32 v223, v231, v45
	ds_bpermute_b32 v224, v231, v46
	ds_bpermute_b32 v225, v231, v47
	s_waitcnt lgkmcnt(0)
	global_store_dwordx4 v[50:51], v[222:225], off
	ds_bpermute_b32 v226, v231, v28
	ds_bpermute_b32 v227, v231, v29
	ds_bpermute_b32 v228, v231, v30
	ds_bpermute_b32 v229, v231, v31
	s_waitcnt lgkmcnt(0)
	global_store_dwordx4 v[34:35], v[226:229], off
	ds_bpermute_b32 v222, v231, v12
	ds_bpermute_b32 v223, v231, v13
	ds_bpermute_b32 v224, v231, v14
	ds_bpermute_b32 v225, v231, v15
	s_waitcnt lgkmcnt(0)
	global_store_dwordx4 v[18:19], v[222:225], off
	ds_bpermute_b32 v226, v231, v8
	ds_bpermute_b32 v227, v231, v9
	ds_bpermute_b32 v228, v231, v10
	ds_bpermute_b32 v229, v231, v11
	s_waitcnt lgkmcnt(0)
	global_store_dwordx4 v[16:17], v[226:229], off offset:256
	s_cbranch_vccnz .LBB0_515
	s_andn2_b64 vcc, exec, s[36:37]
	s_cbranch_vccnz .LBB0_514
	s_mov_b32 s100, 1
	s_branch .LBB0_514

.LBB0_693:
	s_ashr_i32 s75, s74, 31
	s_lshl_b64 s[16:17], s[74:75], 20
	s_add_u32 s84, s14, s16
	s_addc_u32 s85, s15, s17
	s_and_b64 s[16:17], s[36:37], exec
	s_cselect_b32 s16, s85, s89
	s_cselect_b32 s17, s84, s88
	s_ashr_i32 s73, s72, 31
	s_lshl_b64 s[50:51], s[72:73], 20
	s_add_u32 s86, s23, s50
	s_addc_u32 s87, s29, s51
	s_and_b64 s[50:51], s[36:37], exec
	s_cselect_b32 s50, s87, s91
	s_cselect_b32 s51, s86, s90
	s_add_u32 s88, s88, 0x80080
	s_addc_u32 s89, s89, 0
	s_add_u32 s54, s90, 0x100
	s_addc_u32 s55, s91, 0
	s_mov_b32 s56, -2
	v_mov_b64_e32 v[4:5], 0
	v_mov_b64_e32 v[6:7], 0
	v_mov_b64_e32 v[8:9], 0
	v_mov_b64_e32 v[10:11], 0
	v_mov_b64_e32 v[12:13], 0
	v_mov_b64_e32 v[14:15], 0
	v_mov_b64_e32 v[16:17], 0
	v_mov_b64_e32 v[18:19], 0
	v_mov_b64_e32 v[20:21], 0
	v_mov_b64_e32 v[22:23], 0
	v_mov_b64_e32 v[24:25], 0
	v_mov_b64_e32 v[26:27], 0
	v_mov_b64_e32 v[28:29], 0
	v_mov_b64_e32 v[30:31], 0
	v_mov_b64_e32 v[32:33], 0
	v_mov_b64_e32 v[34:35], 0
	v_mov_b64_e32 v[36:37], 0
	v_mov_b64_e32 v[38:39], 0
	v_mov_b64_e32 v[40:41], 0
	v_mov_b64_e32 v[42:43], 0
	v_mov_b64_e32 v[44:45], 0
	v_mov_b64_e32 v[46:47], 0
	v_mov_b64_e32 v[48:49], 0
	v_mov_b64_e32 v[50:51], 0
	v_mov_b64_e32 v[52:53], 0
	v_mov_b64_e32 v[54:55], 0
	v_mov_b64_e32 v[56:57], 0
	v_mov_b64_e32 v[58:59], 0
	v_mov_b64_e32 v[60:61], 0
	v_mov_b64_e32 v[62:63], 0
	v_mov_b64_e32 v[64:65], 0
	v_mov_b64_e32 v[66:67], 0
	v_mov_b64_e32 v[68:69], 0
	v_mov_b64_e32 v[70:71], 0
	v_mov_b64_e32 v[72:73], 0
	v_mov_b64_e32 v[74:75], 0
	v_mov_b64_e32 v[76:77], 0
	v_mov_b64_e32 v[78:79], 0
	v_mov_b64_e32 v[80:81], 0
	v_mov_b64_e32 v[82:83], 0
	v_mov_b64_e32 v[84:85], 0
	v_mov_b64_e32 v[86:87], 0
	v_mov_b64_e32 v[88:89], 0
	v_mov_b64_e32 v[90:91], 0
	v_mov_b64_e32 v[92:93], 0
	v_mov_b64_e32 v[94:95], 0
	v_mov_b64_e32 v[96:97], 0
	v_mov_b64_e32 v[98:99], 0
	v_mov_b64_e32 v[100:101], 0
	v_mov_b64_e32 v[102:103], 0
	v_mov_b64_e32 v[104:105], 0
	v_mov_b64_e32 v[106:107], 0
	v_mov_b64_e32 v[108:109], 0
	v_mov_b64_e32 v[110:111], 0
	v_mov_b64_e32 v[112:113], 0
	v_mov_b64_e32 v[114:115], 0
	v_mov_b64_e32 v[116:117], 0
	v_mov_b64_e32 v[118:119], 0
	v_mov_b64_e32 v[120:121], 0
	v_mov_b64_e32 v[122:123], 0
	v_mov_b64_e32 v[124:125], 0
	v_mov_b64_e32 v[126:127], 0
	v_mov_b64_e32 v[128:129], 0
	v_mov_b64_e32 v[130:131], 0
	v_add_u32_e32 v246, 0x10000, v144
	v_add_u32_e32 v247, 0x14000, v144
	v_add_u32_e32 v248, 0x18000, v144
	v_add_u32_e32 v249, 0x1c000, v144
	s_cmp_eq_u32 s100, 0
	s_cbranch_scc1 .Lrs5
	s_barrier
	s_mov_b32 s100, 0
.Lrs5:
.LBB0_694:
	s_add_u32 s57, s88, 0xfff80080
	s_addc_u32 s73, s89, -1
	s_add_i32 m0, s60, 0xc000
	s_add_i32 s75, s60, 0xe000
	global_load_lds_dwordx4 v138, s[88:89]
	s_mov_b32 m0, s75
	s_cmp_eq_u32 s56, 28
	global_load_lds_dwordx4 v140, s[88:89]
	s_cselect_b32 vcc_hi, s16, s73
	s_cselect_b32 vcc_lo, s17, s57
	s_cselect_b32 s91, s50, s55
	s_cselect_b32 s90, s51, s54
	ds_read_b128 v[148:151], v246
	ds_read_b128 v[152:155], v246 offset:1024
	ds_read_b128 v[156:159], v246 offset:2048
	ds_read_b128 v[160:163], v246 offset:3072
	ds_read_b128 v[164:167], v247
	ds_read_b128 v[168:171], v247 offset:1024
	ds_read_b128 v[172:175], v247 offset:2048
	ds_read_b128 v[176:179], v247 offset:3072
	ds_read_b128 v[180:183], v146
	ds_read_b128 v[184:187], v146 offset:1024
	ds_read_b128 v[188:191], v146 offset:2048
	ds_read_b128 v[192:195], v146 offset:3072
	ds_read_b128 v[196:199], v146 offset:4096
	ds_read_b128 v[200:203], v146 offset:5120
	ds_read_b128 v[210:213], v146 offset:6144
	ds_read_b128 v[214:217], v146 offset:7168
	s_waitcnt vmcnt(8)
	s_waitcnt lgkmcnt(0)
	s_setprio 1
	s_barrier
	v_mfma_f32_16x16x32_bf16 v[128:131], v[148:151], v[180:183], v[128:131]
	v_mfma_f32_16x16x32_bf16 v[124:127], v[156:159], v[180:183], v[124:127]
	v_mfma_f32_16x16x32_bf16 v[112:115], v[148:151], v[188:191], v[112:115]
	v_mfma_f32_16x16x32_bf16 v[108:111], v[156:159], v[188:191], v[108:111]
	v_mfma_f32_16x16x32_bf16 v[96:99], v[148:151], v[196:199], v[96:99]
	v_mfma_f32_16x16x32_bf16 v[92:95], v[156:159], v[196:199], v[92:95]
	v_mfma_f32_16x16x32_bf16 v[80:83], v[148:151], v[210:213], v[80:83]
	v_mfma_f32_16x16x32_bf16 v[76:79], v[156:159], v[210:213], v[76:79]
	v_mfma_f32_16x16x32_bf16 v[128:131], v[152:155], v[184:187], v[128:131]
	v_mfma_f32_16x16x32_bf16 v[124:127], v[160:163], v[184:187], v[124:127]
	v_mfma_f32_16x16x32_bf16 v[112:115], v[152:155], v[192:195], v[112:115]
	v_mfma_f32_16x16x32_bf16 v[108:111], v[160:163], v[192:195], v[108:111]
	v_mfma_f32_16x16x32_bf16 v[96:99], v[152:155], v[200:203], v[96:99]
	v_mfma_f32_16x16x32_bf16 v[92:95], v[160:163], v[200:203], v[92:95]
	v_mfma_f32_16x16x32_bf16 v[80:83], v[152:155], v[214:217], v[80:83]
	v_mfma_f32_16x16x32_bf16 v[76:79], v[160:163], v[214:217], v[76:79]
	v_mfma_f32_16x16x32_bf16 v[120:123], v[164:167], v[180:183], v[120:123]
	v_mfma_f32_16x16x32_bf16 v[116:119], v[172:175], v[180:183], v[116:119]
	v_mfma_f32_16x16x32_bf16 v[104:107], v[164:167], v[188:191], v[104:107]
	v_mfma_f32_16x16x32_bf16 v[100:103], v[172:175], v[188:191], v[100:103]
	v_mfma_f32_16x16x32_bf16 v[88:91], v[164:167], v[196:199], v[88:91]
	v_mfma_f32_16x16x32_bf16 v[84:87], v[172:175], v[196:199], v[84:87]
	v_mfma_f32_16x16x32_bf16 v[72:75], v[164:167], v[210:213], v[72:75]
	v_mfma_f32_16x16x32_bf16 v[68:71], v[172:175], v[210:213], v[68:71]
	v_mfma_f32_16x16x32_bf16 v[120:123], v[168:171], v[184:187], v[120:123]
	v_mfma_f32_16x16x32_bf16 v[116:119], v[176:179], v[184:187], v[116:119]
	v_mfma_f32_16x16x32_bf16 v[104:107], v[168:171], v[192:195], v[104:107]
	v_mfma_f32_16x16x32_bf16 v[100:103], v[176:179], v[192:195], v[100:103]
	v_mfma_f32_16x16x32_bf16 v[88:91], v[168:171], v[200:203], v[88:91]
	v_mfma_f32_16x16x32_bf16 v[84:87], v[176:179], v[200:203], v[84:87]
	v_mfma_f32_16x16x32_bf16 v[72:75], v[168:171], v[214:217], v[72:75]
	v_mfma_f32_16x16x32_bf16 v[68:71], v[176:179], v[214:217], v[68:71]
	s_barrier
	s_setprio 0
	s_add_i32 s57, s33, s35
	s_mov_b32 m0, s57
	s_nop 0
	global_load_lds_dwordx4 v2, s[90:91]
	s_add_i32 m0, s57, 0x2000
	s_add_u32 s76, s90, 0x80000
	s_addc_u32 s77, s91, 0
	s_add_i32 s57, s96, s35
	global_load_lds_dwordx4 v132, s[90:91]
	s_mov_b32 m0, s57
	s_nop 0
	global_load_lds_dwordx4 v2, s[76:77]
	s_add_i32 m0, s57, 0x2000
	s_nop 0
	global_load_lds_dwordx4 v132, s[76:77]
	s_mov_b32 m0, s60
	s_nop 0
	global_load_lds_dwordx4 v136, vcc
	s_mov_b32 m0, s61
	s_nop 0
	global_load_lds_dwordx4 v134, vcc
	ds_read_b128 v[180:183], v146 offset:16384
	ds_read_b128 v[184:187], v146 offset:17408
	ds_read_b128 v[188:191], v146 offset:18432
	ds_read_b128 v[192:195], v146 offset:19456
	ds_read_b128 v[196:199], v146 offset:20480
	ds_read_b128 v[200:203], v146 offset:21504
	ds_read_b128 v[210:213], v146 offset:22528
	ds_read_b128 v[214:217], v146 offset:23552
	s_waitcnt vmcnt(8)
	s_waitcnt lgkmcnt(0)
	s_setprio 1
	s_barrier
	v_mfma_f32_16x16x32_bf16 v[64:67], v[148:151], v[180:183], v[64:67]
	v_mfma_f32_16x16x32_bf16 v[60:63], v[156:159], v[180:183], v[60:63]
	v_mfma_f32_16x16x32_bf16 v[48:51], v[148:151], v[188:191], v[48:51]
	v_mfma_f32_16x16x32_bf16 v[44:47], v[156:159], v[188:191], v[44:47]
	v_mfma_f32_16x16x32_bf16 v[32:35], v[148:151], v[196:199], v[32:35]
	v_mfma_f32_16x16x32_bf16 v[28:31], v[156:159], v[196:199], v[28:31]
	v_mfma_f32_16x16x32_bf16 v[16:19], v[148:151], v[210:213], v[16:19]
	v_mfma_f32_16x16x32_bf16 v[12:15], v[156:159], v[210:213], v[12:15]
	v_mfma_f32_16x16x32_bf16 v[64:67], v[152:155], v[184:187], v[64:67]
	v_mfma_f32_16x16x32_bf16 v[60:63], v[160:163], v[184:187], v[60:63]
	v_mfma_f32_16x16x32_bf16 v[48:51], v[152:155], v[192:195], v[48:51]
	v_mfma_f32_16x16x32_bf16 v[44:47], v[160:163], v[192:195], v[44:47]
	v_mfma_f32_16x16x32_bf16 v[32:35], v[152:155], v[200:203], v[32:35]
	v_mfma_f32_16x16x32_bf16 v[28:31], v[160:163], v[200:203], v[28:31]
	v_mfma_f32_16x16x32_bf16 v[16:19], v[152:155], v[214:217], v[16:19]
	v_mfma_f32_16x16x32_bf16 v[12:15], v[160:163], v[214:217], v[12:15]
	v_mfma_f32_16x16x32_bf16 v[56:59], v[164:167], v[180:183], v[56:59]
	v_mfma_f32_16x16x32_bf16 v[52:55], v[172:175], v[180:183], v[52:55]
	v_mfma_f32_16x16x32_bf16 v[40:43], v[164:167], v[188:191], v[40:43]
	v_mfma_f32_16x16x32_bf16 v[36:39], v[172:175], v[188:191], v[36:39]
	v_mfma_f32_16x16x32_bf16 v[24:27], v[164:167], v[196:199], v[24:27]
	v_mfma_f32_16x16x32_bf16 v[20:23], v[172:175], v[196:199], v[20:23]
	v_mfma_f32_16x16x32_bf16 v[8:11], v[164:167], v[210:213], v[8:11]
	v_mfma_f32_16x16x32_bf16 v[4:7], v[172:175], v[210:213], v[4:7]
	v_mfma_f32_16x16x32_bf16 v[56:59], v[168:171], v[184:187], v[56:59]
	v_mfma_f32_16x16x32_bf16 v[52:55], v[176:179], v[184:187], v[52:55]
	v_mfma_f32_16x16x32_bf16 v[40:43], v[168:171], v[192:195], v[40:43]
	v_mfma_f32_16x16x32_bf16 v[36:39], v[176:179], v[192:195], v[36:39]
	v_mfma_f32_16x16x32_bf16 v[24:27], v[168:171], v[200:203], v[24:27]
	v_mfma_f32_16x16x32_bf16 v[20:23], v[176:179], v[200:203], v[20:23]
	v_mfma_f32_16x16x32_bf16 v[8:11], v[168:171], v[214:217], v[8:11]
	v_mfma_f32_16x16x32_bf16 v[4:7], v[176:179], v[214:217], v[4:7]
	s_barrier
	s_setprio 0
	s_add_u32 s76, vcc_lo, 0x80000
	s_addc_u32 s77, vcc_hi, 0
	s_mov_b32 m0, s62
	s_nop 0
	global_load_lds_dwordx4 v136, s[76:77]
	s_mov_b32 m0, s63
	s_nop 0
	global_load_lds_dwordx4 v134, s[76:77]
	ds_read_b128 v[148:151], v248
	ds_read_b128 v[152:155], v248 offset:1024
	ds_read_b128 v[156:159], v248 offset:2048
	ds_read_b128 v[160:163], v248 offset:3072
	ds_read_b128 v[164:167], v249
	ds_read_b128 v[168:171], v249 offset:1024
	ds_read_b128 v[172:175], v249 offset:2048
	ds_read_b128 v[176:179], v249 offset:3072
	ds_read_b128 v[180:183], v146 offset:32768
	ds_read_b128 v[184:187], v146 offset:33792
	ds_read_b128 v[188:191], v146 offset:34816
	ds_read_b128 v[192:195], v146 offset:35840
	ds_read_b128 v[196:199], v146 offset:36864
	ds_read_b128 v[200:203], v146 offset:37888
	ds_read_b128 v[210:213], v146 offset:38912
	ds_read_b128 v[214:217], v146 offset:39936
	s_waitcnt vmcnt(8)
	s_waitcnt lgkmcnt(0)
	s_setprio 1
	s_barrier
	v_mfma_f32_16x16x32_bf16 v[128:131], v[148:151], v[180:183], v[128:131]
	v_mfma_f32_16x16x32_bf16 v[124:127], v[156:159], v[180:183], v[124:127]
	v_mfma_f32_16x16x32_bf16 v[112:115], v[148:151], v[188:191], v[112:115]
	v_mfma_f32_16x16x32_bf16 v[108:111], v[156:159], v[188:191], v[108:111]
	v_mfma_f32_16x16x32_bf16 v[96:99], v[148:151], v[196:199], v[96:99]
	v_mfma_f32_16x16x32_bf16 v[92:95], v[156:159], v[196:199], v[92:95]
	v_mfma_f32_16x16x32_bf16 v[80:83], v[148:151], v[210:213], v[80:83]
	v_mfma_f32_16x16x32_bf16 v[76:79], v[156:159], v[210:213], v[76:79]
	v_mfma_f32_16x16x32_bf16 v[128:131], v[152:155], v[184:187], v[128:131]
	v_mfma_f32_16x16x32_bf16 v[124:127], v[160:163], v[184:187], v[124:127]
	v_mfma_f32_16x16x32_bf16 v[112:115], v[152:155], v[192:195], v[112:115]
	v_mfma_f32_16x16x32_bf16 v[108:111], v[160:163], v[192:195], v[108:111]
	v_mfma_f32_16x16x32_bf16 v[96:99], v[152:155], v[200:203], v[96:99]
	v_mfma_f32_16x16x32_bf16 v[92:95], v[160:163], v[200:203], v[92:95]
	v_mfma_f32_16x16x32_bf16 v[80:83], v[152:155], v[214:217], v[80:83]
	v_mfma_f32_16x16x32_bf16 v[76:79], v[160:163], v[214:217], v[76:79]
	v_mfma_f32_16x16x32_bf16 v[120:123], v[164:167], v[180:183], v[120:123]
	v_mfma_f32_16x16x32_bf16 v[116:119], v[172:175], v[180:183], v[116:119]
	v_mfma_f32_16x16x32_bf16 v[104:107], v[164:167], v[188:191], v[104:107]
	v_mfma_f32_16x16x32_bf16 v[100:103], v[172:175], v[188:191], v[100:103]
	v_mfma_f32_16x16x32_bf16 v[88:91], v[164:167], v[196:199], v[88:91]
	v_mfma_f32_16x16x32_bf16 v[84:87], v[172:175], v[196:199], v[84:87]
	v_mfma_f32_16x16x32_bf16 v[72:75], v[164:167], v[210:213], v[72:75]
	v_mfma_f32_16x16x32_bf16 v[68:71], v[172:175], v[210:213], v[68:71]
	v_mfma_f32_16x16x32_bf16 v[120:123], v[168:171], v[184:187], v[120:123]
	v_mfma_f32_16x16x32_bf16 v[116:119], v[176:179], v[184:187], v[116:119]
	v_mfma_f32_16x16x32_bf16 v[104:107], v[168:171], v[192:195], v[104:107]
	v_mfma_f32_16x16x32_bf16 v[100:103], v[176:179], v[192:195], v[100:103]
	v_mfma_f32_16x16x32_bf16 v[88:91], v[168:171], v[200:203], v[88:91]
	v_mfma_f32_16x16x32_bf16 v[84:87], v[176:179], v[200:203], v[84:87]
	v_mfma_f32_16x16x32_bf16 v[72:75], v[168:171], v[214:217], v[72:75]
	v_mfma_f32_16x16x32_bf16 v[68:71], v[176:179], v[214:217], v[68:71]
	s_barrier
	s_setprio 0
	s_add_i32 s57, s97, s35
	s_mov_b32 m0, s57
	s_nop 0
	s_add_u32 s98, s90, 0x80
	s_addc_u32 s99, s91, 0
	s_nop 0
	global_load_lds_dwordx4 v2, s[98:99]
	s_add_i32 m0, s57, 0x2000
	s_add_u32 s76, s90, 0x80080
	s_addc_u32 s77, s91, 0
	s_add_i32 s57, s48, s35
	global_load_lds_dwordx4 v132, s[98:99]
	s_mov_b32 m0, s57
	s_nop 0
	global_load_lds_dwordx4 v2, s[76:77]
	s_add_i32 m0, s57, 0x2000
	s_nop 0
	global_load_lds_dwordx4 v132, s[76:77]
	s_mov_b32 m0, s64
	s_nop 0
	s_add_u32 s98, vcc_lo, 0x80
	s_addc_u32 s99, vcc_hi, 0
	s_nop 0
	global_load_lds_dwordx4 v136, s[98:99]
	s_mov_b32 m0, s58
	s_nop 0
	global_load_lds_dwordx4 v134, s[98:99]
	ds_read_b128 v[180:183], v146 offset:49152
	ds_read_b128 v[184:187], v146 offset:50176
	ds_read_b128 v[188:191], v146 offset:51200
	ds_read_b128 v[192:195], v146 offset:52224
	ds_read_b128 v[196:199], v146 offset:53248
	ds_read_b128 v[200:203], v146 offset:54272
	ds_read_b128 v[210:213], v146 offset:55296
	ds_read_b128 v[214:217], v146 offset:56320
	s_waitcnt vmcnt(8)
	s_waitcnt lgkmcnt(0)
	s_setprio 1
	s_barrier
	v_mfma_f32_16x16x32_bf16 v[64:67], v[148:151], v[180:183], v[64:67]
	v_mfma_f32_16x16x32_bf16 v[60:63], v[156:159], v[180:183], v[60:63]
	v_mfma_f32_16x16x32_bf16 v[48:51], v[148:151], v[188:191], v[48:51]
	v_mfma_f32_16x16x32_bf16 v[44:47], v[156:159], v[188:191], v[44:47]
	v_mfma_f32_16x16x32_bf16 v[32:35], v[148:151], v[196:199], v[32:35]
	v_mfma_f32_16x16x32_bf16 v[28:31], v[156:159], v[196:199], v[28:31]
	v_mfma_f32_16x16x32_bf16 v[16:19], v[148:151], v[210:213], v[16:19]
	v_mfma_f32_16x16x32_bf16 v[12:15], v[156:159], v[210:213], v[12:15]
	v_mfma_f32_16x16x32_bf16 v[64:67], v[152:155], v[184:187], v[64:67]
	v_mfma_f32_16x16x32_bf16 v[60:63], v[160:163], v[184:187], v[60:63]
	v_mfma_f32_16x16x32_bf16 v[48:51], v[152:155], v[192:195], v[48:51]
	v_mfma_f32_16x16x32_bf16 v[44:47], v[160:163], v[192:195], v[44:47]
	v_mfma_f32_16x16x32_bf16 v[32:35], v[152:155], v[200:203], v[32:35]
	v_mfma_f32_16x16x32_bf16 v[28:31], v[160:163], v[200:203], v[28:31]
	v_mfma_f32_16x16x32_bf16 v[16:19], v[152:155], v[214:217], v[16:19]
	v_mfma_f32_16x16x32_bf16 v[12:15], v[160:163], v[214:217], v[12:15]
	v_mfma_f32_16x16x32_bf16 v[56:59], v[164:167], v[180:183], v[56:59]
	v_mfma_f32_16x16x32_bf16 v[52:55], v[172:175], v[180:183], v[52:55]
	v_mfma_f32_16x16x32_bf16 v[40:43], v[164:167], v[188:191], v[40:43]
	v_mfma_f32_16x16x32_bf16 v[36:39], v[172:175], v[188:191], v[36:39]
	v_mfma_f32_16x16x32_bf16 v[24:27], v[164:167], v[196:199], v[24:27]
	v_mfma_f32_16x16x32_bf16 v[20:23], v[172:175], v[196:199], v[20:23]
	v_mfma_f32_16x16x32_bf16 v[8:11], v[164:167], v[210:213], v[8:11]
	v_mfma_f32_16x16x32_bf16 v[4:7], v[172:175], v[210:213], v[4:7]
	v_mfma_f32_16x16x32_bf16 v[56:59], v[168:171], v[184:187], v[56:59]
	v_mfma_f32_16x16x32_bf16 v[52:55], v[176:179], v[184:187], v[52:55]
	v_mfma_f32_16x16x32_bf16 v[40:43], v[168:171], v[192:195], v[40:43]
	v_mfma_f32_16x16x32_bf16 v[36:39], v[176:179], v[192:195], v[36:39]
	v_mfma_f32_16x16x32_bf16 v[24:27], v[168:171], v[200:203], v[24:27]
	v_mfma_f32_16x16x32_bf16 v[20:23], v[176:179], v[200:203], v[20:23]
	v_mfma_f32_16x16x32_bf16 v[8:11], v[168:171], v[214:217], v[8:11]
	v_mfma_f32_16x16x32_bf16 v[4:7], v[176:179], v[214:217], v[4:7]
	s_barrier
	s_setprio 0
	s_add_i32 s56, s56, 2
	s_add_u32 s88, s88, 0x100
	s_addc_u32 s89, s89, 0
	s_add_u32 s54, s54, 0x100
	s_addc_u32 s55, s55, 0
	s_cmp_gt_u32 s56, 29
	s_cbranch_scc0 .LBB0_694
	s_and_b64 vcc, exec, s[68:69]
	s_cbranch_vccz .LBB0_697
	s_barrier
.LBB0_697:
	v_max_f32_e32 v124, 0, v124
	v_max_f32_e32 v125, 0, v125
	v_pk_mul_f32 v[152:153], v[124:125], v[124:125]
	v_lshl_or_b32 v142, s12, 8, v145
	v_lshl_add_u32 v148, s13, 8, v1
	v_max_f32_e32 v126, 0, v126
	v_ashrrev_i32_e32 v143, 31, v142
	v_ashrrev_i32_e32 v149, 31, v148
	v_max_f32_e32 v128, 0, v128
	v_max_f32_e32 v129, 0, v129
	v_max_f32_e32 v124, 0, v130
	v_max_f32_e32 v125, 0, v131
	v_max_f32_e32 v127, 0, v127
	v_lshl_add_u64 v[150:151], v[142:143], 1, s[38:39]
	v_lshlrev_b64 v[142:143], 14, v[148:149]
	v_pk_mul_f32 v[128:129], v[128:129], v[128:129]
	v_pk_mul_f32 v[130:131], v[124:125], v[124:125]
	v_pk_mul_f32 v[154:155], v[126:127], v[126:127]
	v_lshl_add_u64 v[142:143], v[150:151], 0, v[142:143]
	v_cvt_pk_bf16_f32 v124, v128, v129
	v_cvt_pk_bf16_f32 v125, v130, v131
	v_cvt_pk_bf16_f32 v126, v152, v153
	v_cvt_pk_bf16_f32 v127, v154, v155
	v_max_f32_e32 v116, 0, v116
	v_max_f32_e32 v117, 0, v117
	ds_bpermute_b32 v222, v231, v124
	ds_bpermute_b32 v223, v231, v125
	ds_bpermute_b32 v224, v231, v126
	ds_bpermute_b32 v225, v231, v127
	v_pk_mul_f32 v[124:125], v[116:117], v[116:117]
	v_max_f32_e32 v118, 0, v118
	v_max_f32_e32 v120, 0, v120
	v_max_f32_e32 v121, 0, v121
	v_max_f32_e32 v116, 0, v122
	v_max_f32_e32 v117, 0, v123
	v_max_f32_e32 v119, 0, v119
	v_pk_mul_f32 v[120:121], v[120:121], v[120:121]
	v_pk_mul_f32 v[122:123], v[116:117], v[116:117]
	v_pk_mul_f32 v[126:127], v[118:119], v[118:119]
	v_cvt_pk_bf16_f32 v116, v120, v121
	v_cvt_pk_bf16_f32 v117, v122, v123
	v_cvt_pk_bf16_f32 v118, v124, v125
	v_cvt_pk_bf16_f32 v119, v126, v127
	v_max_f32_e32 v108, 0, v108
	v_max_f32_e32 v109, 0, v109
	s_waitcnt lgkmcnt(0)
	global_store_dwordx4 v[142:143], v[222:225], off
	ds_bpermute_b32 v226, v231, v116
	ds_bpermute_b32 v227, v231, v117
	ds_bpermute_b32 v228, v231, v118
	ds_bpermute_b32 v229, v231, v119
	v_pk_mul_f32 v[118:119], v[108:109], v[108:109]
	v_or_b32_e32 v116, 16, v148
	v_max_f32_e32 v110, 0, v110
	v_ashrrev_i32_e32 v117, 31, v116
	v_max_f32_e32 v112, 0, v112
	v_max_f32_e32 v113, 0, v113
	v_max_f32_e32 v108, 0, v114
	v_max_f32_e32 v109, 0, v115
	v_max_f32_e32 v111, 0, v111
	v_lshlrev_b64 v[116:117], 14, v[116:117]
	v_pk_mul_f32 v[112:113], v[112:113], v[112:113]
	v_pk_mul_f32 v[114:115], v[108:109], v[108:109]
	v_pk_mul_f32 v[120:121], v[110:111], v[110:111]
	v_lshl_add_u64 v[116:117], v[150:151], 0, v[116:117]
	v_cvt_pk_bf16_f32 v108, v112, v113
	v_cvt_pk_bf16_f32 v109, v114, v115
	v_cvt_pk_bf16_f32 v110, v118, v119
	v_cvt_pk_bf16_f32 v111, v120, v121
	v_max_f32_e32 v100, 0, v100
	v_max_f32_e32 v101, 0, v101
	s_waitcnt lgkmcnt(0)
	global_store_dwordx4 v[142:143], v[226:229], off offset:256
	ds_bpermute_b32 v222, v231, v108
	ds_bpermute_b32 v223, v231, v109
	ds_bpermute_b32 v224, v231, v110
	ds_bpermute_b32 v225, v231, v111
	v_pk_mul_f32 v[108:109], v[100:101], v[100:101]
	v_max_f32_e32 v102, 0, v102
	v_max_f32_e32 v104, 0, v104
	v_max_f32_e32 v105, 0, v105
	v_max_f32_e32 v100, 0, v106
	v_max_f32_e32 v101, 0, v107
	v_max_f32_e32 v103, 0, v103
	v_pk_mul_f32 v[104:105], v[104:105], v[104:105]
	v_pk_mul_f32 v[106:107], v[100:101], v[100:101]
	v_pk_mul_f32 v[110:111], v[102:103], v[102:103]
	v_cvt_pk_bf16_f32 v100, v104, v105
	v_cvt_pk_bf16_f32 v101, v106, v107
	v_cvt_pk_bf16_f32 v102, v108, v109
	v_cvt_pk_bf16_f32 v103, v110, v111
	v_max_f32_e32 v92, 0, v92
	v_max_f32_e32 v93, 0, v93
	s_waitcnt lgkmcnt(0)
	global_store_dwordx4 v[116:117], v[222:225], off
	ds_bpermute_b32 v226, v231, v100
	ds_bpermute_b32 v227, v231, v101
	ds_bpermute_b32 v228, v231, v102
	ds_bpermute_b32 v229, v231, v103
	v_pk_mul_f32 v[102:103], v[92:93], v[92:93]
	v_or_b32_e32 v100, 32, v148
	v_max_f32_e32 v94, 0, v94
	v_ashrrev_i32_e32 v101, 31, v100
	v_max_f32_e32 v96, 0, v96
	v_max_f32_e32 v97, 0, v97
	v_max_f32_e32 v92, 0, v98
	v_max_f32_e32 v93, 0, v99
	v_max_f32_e32 v95, 0, v95
	v_lshlrev_b64 v[100:101], 14, v[100:101]
	v_pk_mul_f32 v[96:97], v[96:97], v[96:97]
	v_pk_mul_f32 v[98:99], v[92:93], v[92:93]
	v_pk_mul_f32 v[104:105], v[94:95], v[94:95]
	v_lshl_add_u64 v[100:101], v[150:151], 0, v[100:101]
	v_cvt_pk_bf16_f32 v92, v96, v97
	v_cvt_pk_bf16_f32 v93, v98, v99
	v_cvt_pk_bf16_f32 v94, v102, v103
	v_cvt_pk_bf16_f32 v95, v104, v105
	v_max_f32_e32 v84, 0, v84
	v_max_f32_e32 v85, 0, v85
	s_waitcnt lgkmcnt(0)
	global_store_dwordx4 v[116:117], v[226:229], off offset:256
	ds_bpermute_b32 v222, v231, v92
	ds_bpermute_b32 v223, v231, v93
	ds_bpermute_b32 v224, v231, v94
	ds_bpermute_b32 v225, v231, v95
	v_pk_mul_f32 v[92:93], v[84:85], v[84:85]
	v_max_f32_e32 v86, 0, v86
	v_max_f32_e32 v88, 0, v88
	v_max_f32_e32 v89, 0, v89
	v_max_f32_e32 v84, 0, v90
	v_max_f32_e32 v85, 0, v91
	v_max_f32_e32 v87, 0, v87
	v_pk_mul_f32 v[88:89], v[88:89], v[88:89]
	v_pk_mul_f32 v[90:91], v[84:85], v[84:85]
	v_pk_mul_f32 v[94:95], v[86:87], v[86:87]
	v_cvt_pk_bf16_f32 v84, v88, v89
	v_cvt_pk_bf16_f32 v85, v90, v91
	v_cvt_pk_bf16_f32 v86, v92, v93
	v_cvt_pk_bf16_f32 v87, v94, v95
	v_max_f32_e32 v76, 0, v76
	v_max_f32_e32 v77, 0, v77
	s_waitcnt lgkmcnt(0)
	global_store_dwordx4 v[100:101], v[222:225], off
	ds_bpermute_b32 v226, v231, v84
	ds_bpermute_b32 v227, v231, v85
	ds_bpermute_b32 v228, v231, v86
	ds_bpermute_b32 v229, v231, v87
	v_pk_mul_f32 v[86:87], v[76:77], v[76:77]
	v_or_b32_e32 v84, 48, v148
	v_max_f32_e32 v78, 0, v78
	v_ashrrev_i32_e32 v85, 31, v84
	v_max_f32_e32 v80, 0, v80
	v_max_f32_e32 v81, 0, v81
	v_max_f32_e32 v76, 0, v82
	v_max_f32_e32 v77, 0, v83
	v_max_f32_e32 v79, 0, v79
	v_lshlrev_b64 v[84:85], 14, v[84:85]
	v_pk_mul_f32 v[80:81], v[80:81], v[80:81]
	v_pk_mul_f32 v[82:83], v[76:77], v[76:77]
	v_pk_mul_f32 v[88:89], v[78:79], v[78:79]
	v_lshl_add_u64 v[84:85], v[150:151], 0, v[84:85]
	v_cvt_pk_bf16_f32 v76, v80, v81
	v_cvt_pk_bf16_f32 v77, v82, v83
	v_cvt_pk_bf16_f32 v78, v86, v87
	v_cvt_pk_bf16_f32 v79, v88, v89
	v_max_f32_e32 v68, 0, v68
	v_max_f32_e32 v69, 0, v69
	s_waitcnt lgkmcnt(0)
	global_store_dwordx4 v[100:101], v[226:229], off offset:256
	ds_bpermute_b32 v222, v231, v76
	ds_bpermute_b32 v223, v231, v77
	ds_bpermute_b32 v224, v231, v78
	ds_bpermute_b32 v225, v231, v79
	v_pk_mul_f32 v[76:77], v[68:69], v[68:69]
	v_max_f32_e32 v70, 0, v70
	v_max_f32_e32 v72, 0, v72
	v_max_f32_e32 v73, 0, v73
	v_max_f32_e32 v68, 0, v74
	v_max_f32_e32 v69, 0, v75
	v_max_f32_e32 v71, 0, v71
	v_pk_mul_f32 v[72:73], v[72:73], v[72:73]
	v_pk_mul_f32 v[74:75], v[68:69], v[68:69]
	v_pk_mul_f32 v[78:79], v[70:71], v[70:71]
	v_cvt_pk_bf16_f32 v68, v72, v73
	v_cvt_pk_bf16_f32 v69, v74, v75
	v_cvt_pk_bf16_f32 v70, v76, v77
	v_cvt_pk_bf16_f32 v71, v78, v79
	v_max_f32_e32 v60, 0, v60
	v_max_f32_e32 v61, 0, v61
	s_waitcnt lgkmcnt(0)
	global_store_dwordx4 v[84:85], v[222:225], off
	ds_bpermute_b32 v226, v231, v68
	ds_bpermute_b32 v227, v231, v69
	ds_bpermute_b32 v228, v231, v70
	ds_bpermute_b32 v229, v231, v71
	v_pk_mul_f32 v[70:71], v[60:61], v[60:61]
	s_mov_b64 s[12:13], 0x200000
	v_max_f32_e32 v64, 0, v64
	v_max_f32_e32 v65, 0, v65
	v_max_f32_e32 v62, 0, v62
	v_lshl_add_u64 v[68:69], v[142:143], 0, s[12:13]
	v_pk_mul_f32 v[64:65], v[64:65], v[64:65]
	v_max_f32_e32 v60, 0, v66
	v_max_f32_e32 v61, 0, v67
	v_max_f32_e32 v63, 0, v63
	s_mov_b32 s12, 0x200000
	v_pk_mul_f32 v[66:67], v[60:61], v[60:61]
	v_pk_mul_f32 v[72:73], v[62:63], v[62:63]
	v_cvt_pk_bf16_f32 v60, v64, v65
	v_add_co_u32_e32 v64, vcc, s12, v142
	v_cvt_pk_bf16_f32 v61, v66, v67
	v_cvt_pk_bf16_f32 v62, v70, v71
	v_cvt_pk_bf16_f32 v63, v72, v73
	v_addc_co_u32_e32 v65, vcc, 0, v143, vcc
	v_max_f32_e32 v52, 0, v52
	v_max_f32_e32 v53, 0, v53
	s_waitcnt lgkmcnt(0)
	global_store_dwordx4 v[84:85], v[226:229], off offset:256
	ds_bpermute_b32 v222, v231, v60
	ds_bpermute_b32 v223, v231, v61
	ds_bpermute_b32 v224, v231, v62
	ds_bpermute_b32 v225, v231, v63
	v_pk_mul_f32 v[60:61], v[52:53], v[52:53]
	v_max_f32_e32 v54, 0, v54
	v_max_f32_e32 v56, 0, v56
	v_max_f32_e32 v57, 0, v57
	v_max_f32_e32 v52, 0, v58
	v_max_f32_e32 v53, 0, v59
	v_max_f32_e32 v55, 0, v55
	v_pk_mul_f32 v[56:57], v[56:57], v[56:57]
	v_pk_mul_f32 v[58:59], v[52:53], v[52:53]
	v_pk_mul_f32 v[62:63], v[54:55], v[54:55]
	v_cvt_pk_bf16_f32 v52, v56, v57
	v_cvt_pk_bf16_f32 v53, v58, v59
	v_cvt_pk_bf16_f32 v54, v60, v61
	v_cvt_pk_bf16_f32 v55, v62, v63
	v_max_f32_e32 v44, 0, v44
	v_max_f32_e32 v45, 0, v45
	s_waitcnt lgkmcnt(0)
	global_store_dwordx4 v[64:65], v[222:225], off
	ds_bpermute_b32 v226, v231, v52
	ds_bpermute_b32 v227, v231, v53
	ds_bpermute_b32 v228, v231, v54
	ds_bpermute_b32 v229, v231, v55
	v_pk_mul_f32 v[54:55], v[44:45], v[44:45]
	s_mov_b64 s[12:13], 0x240000
	v_max_f32_e32 v48, 0, v48
	v_max_f32_e32 v49, 0, v49
	v_max_f32_e32 v46, 0, v46
	v_lshl_add_u64 v[52:53], v[142:143], 0, s[12:13]
	v_pk_mul_f32 v[48:49], v[48:49], v[48:49]
	v_max_f32_e32 v44, 0, v50
	v_max_f32_e32 v45, 0, v51
	v_max_f32_e32 v47, 0, v47
	s_mov_b32 s12, 0x240000
	v_pk_mul_f32 v[50:51], v[44:45], v[44:45]
	v_pk_mul_f32 v[56:57], v[46:47], v[46:47]
	v_cvt_pk_bf16_f32 v44, v48, v49
	v_add_co_u32_e32 v48, vcc, s12, v142
	v_cvt_pk_bf16_f32 v45, v50, v51
	v_cvt_pk_bf16_f32 v46, v54, v55
	v_cvt_pk_bf16_f32 v47, v56, v57
	v_addc_co_u32_e32 v49, vcc, 0, v143, vcc
	v_max_f32_e32 v36, 0, v36
	v_max_f32_e32 v37, 0, v37
	s_waitcnt lgkmcnt(0)
	global_store_dwordx4 v[68:69], v[226:229], off offset:256
	ds_bpermute_b32 v222, v231, v44
	ds_bpermute_b32 v223, v231, v45
	ds_bpermute_b32 v224, v231, v46
	ds_bpermute_b32 v225, v231, v47
	v_pk_mul_f32 v[44:45], v[36:37], v[36:37]
	v_max_f32_e32 v38, 0, v38
	v_max_f32_e32 v40, 0, v40
	v_max_f32_e32 v41, 0, v41
	v_max_f32_e32 v36, 0, v42
	v_max_f32_e32 v37, 0, v43
	v_max_f32_e32 v39, 0, v39
	v_pk_mul_f32 v[40:41], v[40:41], v[40:41]
	v_pk_mul_f32 v[42:43], v[36:37], v[36:37]
	v_pk_mul_f32 v[46:47], v[38:39], v[38:39]
	v_cvt_pk_bf16_f32 v36, v40, v41
	v_cvt_pk_bf16_f32 v37, v42, v43
	v_cvt_pk_bf16_f32 v38, v44, v45
	v_cvt_pk_bf16_f32 v39, v46, v47
	v_max_f32_e32 v28, 0, v28
	v_max_f32_e32 v29, 0, v29
	s_waitcnt lgkmcnt(0)
	global_store_dwordx4 v[48:49], v[222:225], off
	ds_bpermute_b32 v226, v231, v36
	ds_bpermute_b32 v227, v231, v37
	ds_bpermute_b32 v228, v231, v38
	ds_bpermute_b32 v229, v231, v39
	v_pk_mul_f32 v[38:39], v[28:29], v[28:29]
	s_mov_b64 s[12:13], 0x280000
	v_max_f32_e32 v32, 0, v32
	v_max_f32_e32 v33, 0, v33
	v_max_f32_e32 v30, 0, v30
	v_lshl_add_u64 v[36:37], v[142:143], 0, s[12:13]
	v_pk_mul_f32 v[32:33], v[32:33], v[32:33]
	v_max_f32_e32 v28, 0, v34
	v_max_f32_e32 v29, 0, v35
	v_max_f32_e32 v31, 0, v31
	s_mov_b32 s12, 0x280000
	v_pk_mul_f32 v[34:35], v[28:29], v[28:29]
	v_pk_mul_f32 v[40:41], v[30:31], v[30:31]
	v_cvt_pk_bf16_f32 v28, v32, v33
	v_add_co_u32_e32 v32, vcc, s12, v142
	v_cvt_pk_bf16_f32 v29, v34, v35
	v_cvt_pk_bf16_f32 v30, v38, v39
	v_cvt_pk_bf16_f32 v31, v40, v41
	v_addc_co_u32_e32 v33, vcc, 0, v143, vcc
	v_max_f32_e32 v20, 0, v20
	v_max_f32_e32 v21, 0, v21
	s_waitcnt lgkmcnt(0)
	global_store_dwordx4 v[52:53], v[226:229], off offset:256
	ds_bpermute_b32 v222, v231, v28
	ds_bpermute_b32 v223, v231, v29
	ds_bpermute_b32 v224, v231, v30
	ds_bpermute_b32 v225, v231, v31
	v_pk_mul_f32 v[28:29], v[20:21], v[20:21]
	v_max_f32_e32 v22, 0, v22
	v_max_f32_e32 v24, 0, v24
	v_max_f32_e32 v25, 0, v25
	v_max_f32_e32 v20, 0, v26
	v_max_f32_e32 v21, 0, v27
	v_max_f32_e32 v23, 0, v23
	v_pk_mul_f32 v[24:25], v[24:25], v[24:25]
	v_pk_mul_f32 v[26:27], v[20:21], v[20:21]
	v_pk_mul_f32 v[30:31], v[22:23], v[22:23]
	v_cvt_pk_bf16_f32 v20, v24, v25
	v_cvt_pk_bf16_f32 v21, v26, v27
	v_cvt_pk_bf16_f32 v22, v28, v29
	v_cvt_pk_bf16_f32 v23, v30, v31
	v_max_f32_e32 v12, 0, v12
	v_max_f32_e32 v13, 0, v13
	s_waitcnt lgkmcnt(0)
	global_store_dwordx4 v[32:33], v[222:225], off
	ds_bpermute_b32 v226, v231, v20
	ds_bpermute_b32 v227, v231, v21
	ds_bpermute_b32 v228, v231, v22
	ds_bpermute_b32 v229, v231, v23
	v_pk_mul_f32 v[22:23], v[12:13], v[12:13]
	s_mov_b64 s[12:13], 0x2c0000
	v_max_f32_e32 v16, 0, v16
	v_max_f32_e32 v17, 0, v17
	v_max_f32_e32 v14, 0, v14
	v_lshl_add_u64 v[20:21], v[142:143], 0, s[12:13]
	v_pk_mul_f32 v[16:17], v[16:17], v[16:17]
	v_max_f32_e32 v12, 0, v18
	v_max_f32_e32 v13, 0, v19
	v_max_f32_e32 v15, 0, v15
	s_mov_b32 s12, 0x2c0000
	v_pk_mul_f32 v[18:19], v[12:13], v[12:13]
	v_pk_mul_f32 v[24:25], v[14:15], v[14:15]
	v_cvt_pk_bf16_f32 v12, v16, v17
	v_add_co_u32_e32 v16, vcc, s12, v142
	v_cvt_pk_bf16_f32 v13, v18, v19
	v_cvt_pk_bf16_f32 v14, v22, v23
	v_cvt_pk_bf16_f32 v15, v24, v25
	v_addc_co_u32_e32 v17, vcc, 0, v143, vcc
	v_max_f32_e32 v4, 0, v4
	v_max_f32_e32 v5, 0, v5
	s_waitcnt lgkmcnt(0)
	global_store_dwordx4 v[36:37], v[226:229], off offset:256
	ds_bpermute_b32 v222, v231, v12
	ds_bpermute_b32 v223, v231, v13
	ds_bpermute_b32 v224, v231, v14
	ds_bpermute_b32 v225, v231, v15
	v_pk_mul_f32 v[12:13], v[4:5], v[4:5]
	v_max_f32_e32 v6, 0, v6
	v_max_f32_e32 v8, 0, v8
	v_max_f32_e32 v9, 0, v9
	v_max_f32_e32 v4, 0, v10
	v_max_f32_e32 v5, 0, v11
	v_max_f32_e32 v7, 0, v7
	v_pk_mul_f32 v[8:9], v[8:9], v[8:9]
	v_pk_mul_f32 v[10:11], v[4:5], v[4:5]
	v_pk_mul_f32 v[14:15], v[6:7], v[6:7]
	v_cvt_pk_bf16_f32 v4, v8, v9
	v_cvt_pk_bf16_f32 v5, v10, v11
	v_cvt_pk_bf16_f32 v6, v12, v13
	v_cvt_pk_bf16_f32 v7, v14, v15
	s_andn2_b64 vcc, exec, s[36:37]
	s_mov_b64 s[36:37], -1
	s_waitcnt lgkmcnt(0)
	global_store_dwordx4 v[16:17], v[222:225], off
	ds_bpermute_b32 v226, v231, v4
	ds_bpermute_b32 v227, v231, v5
	ds_bpermute_b32 v228, v231, v6
	ds_bpermute_b32 v229, v231, v7
	s_waitcnt lgkmcnt(0)
	global_store_dwordx4 v[20:21], v[226:229], off offset:256
	s_cbranch_vccnz .LBB0_690
	s_andn2_b64 vcc, exec, s[0:1]
	s_cbranch_vccnz .LBB0_689
	s_mov_b32 s100, 1
	s_branch .LBB0_689

.LBB0_762:
	s_add_i32 s23, s51, -2
	s_add_u32 s84, s84, 0x200080
	s_addc_u32 s85, s85, 0
	s_add_u32 s29, s86, 0x100
	s_addc_u32 s35, s87, 0
	s_mov_b32 s55, 0
	v_mov_b64_e32 v[4:5], 0
	v_mov_b64_e32 v[6:7], 0
	v_mov_b64_e32 v[8:9], 0
	v_mov_b64_e32 v[10:11], 0
	v_mov_b64_e32 v[12:13], 0
	v_mov_b64_e32 v[14:15], 0
	v_mov_b64_e32 v[16:17], 0
	v_mov_b64_e32 v[18:19], 0
	v_mov_b64_e32 v[20:21], 0
	v_mov_b64_e32 v[22:23], 0
	v_mov_b64_e32 v[24:25], 0
	v_mov_b64_e32 v[26:27], 0
	v_mov_b64_e32 v[28:29], 0
	v_mov_b64_e32 v[30:31], 0
	v_mov_b64_e32 v[32:33], 0
	v_mov_b64_e32 v[34:35], 0
	v_mov_b64_e32 v[36:37], 0
	v_mov_b64_e32 v[38:39], 0
	v_mov_b64_e32 v[40:41], 0
	v_mov_b64_e32 v[42:43], 0
	v_mov_b64_e32 v[44:45], 0
	v_mov_b64_e32 v[46:47], 0
	v_mov_b64_e32 v[48:49], 0
	v_mov_b64_e32 v[50:51], 0
	v_mov_b64_e32 v[52:53], 0
	v_mov_b64_e32 v[54:55], 0
	v_mov_b64_e32 v[56:57], 0
	v_mov_b64_e32 v[58:59], 0
	v_mov_b64_e32 v[60:61], 0
	v_mov_b64_e32 v[62:63], 0
	v_mov_b64_e32 v[64:65], 0
	v_mov_b64_e32 v[66:67], 0
	v_mov_b64_e32 v[68:69], 0
	v_mov_b64_e32 v[70:71], 0
	v_mov_b64_e32 v[72:73], 0
	v_mov_b64_e32 v[74:75], 0
	v_mov_b64_e32 v[76:77], 0
	v_mov_b64_e32 v[78:79], 0
	v_mov_b64_e32 v[80:81], 0
	v_mov_b64_e32 v[82:83], 0
	v_mov_b64_e32 v[84:85], 0
	v_mov_b64_e32 v[86:87], 0
	v_mov_b64_e32 v[88:89], 0
	v_mov_b64_e32 v[90:91], 0
	v_mov_b64_e32 v[92:93], 0
	v_mov_b64_e32 v[94:95], 0
	v_mov_b64_e32 v[96:97], 0
	v_mov_b64_e32 v[98:99], 0
	v_mov_b64_e32 v[100:101], 0
	v_mov_b64_e32 v[102:103], 0
	v_mov_b64_e32 v[104:105], 0
	v_mov_b64_e32 v[106:107], 0
	v_mov_b64_e32 v[108:109], 0
	v_mov_b64_e32 v[110:111], 0
	v_mov_b64_e32 v[112:113], 0
	v_mov_b64_e32 v[114:115], 0
	v_mov_b64_e32 v[116:117], 0
	v_mov_b64_e32 v[118:119], 0
	v_mov_b64_e32 v[120:121], 0
	v_mov_b64_e32 v[122:123], 0
	v_mov_b64_e32 v[124:125], 0
	v_mov_b64_e32 v[126:127], 0
	v_mov_b64_e32 v[128:129], 0
	v_mov_b64_e32 v[130:131], 0
	v_add_u32_e32 v246, 0x10000, v142
	v_add_u32_e32 v247, 0x14000, v142
	v_add_u32_e32 v248, 0x18000, v142
	v_add_u32_e32 v249, 0x1c000, v142
	s_cmp_eq_u32 s100, 0
	s_cbranch_scc1 .Lrs6
	s_barrier
	s_mov_b32 s100, 0
.Lrs6:
.LBB0_763:
	s_add_i32 s56, s55, 2
	s_add_u32 s57, s84, 0xffe00080
	s_addc_u32 s62, s85, -1
	s_add_i32 m0, s16, 0xc000
	s_add_i32 s63, s16, 0xe000
	global_load_lds_dwordx4 v138, s[84:85]
	s_mov_b32 m0, s63
	s_cmp_eq_u32 s23, s55
	global_load_lds_dwordx4 v140, s[84:85]
	s_cselect_b32 s89, s73, s62
	s_cselect_b32 s88, s72, s57
	s_cselect_b32 s87, s75, s35
	s_cselect_b32 s86, s74, s29
	ds_read_b128 v[146:149], v246
	ds_read_b128 v[150:153], v246 offset:1024
	ds_read_b128 v[154:157], v246 offset:2048
	ds_read_b128 v[158:161], v246 offset:3072
	ds_read_b128 v[162:165], v247
	ds_read_b128 v[166:169], v247 offset:1024
	ds_read_b128 v[170:173], v247 offset:2048
	ds_read_b128 v[174:177], v247 offset:3072
	ds_read_b128 v[178:181], v144
	ds_read_b128 v[182:185], v144 offset:1024
	ds_read_b128 v[186:189], v144 offset:2048
	ds_read_b128 v[190:193], v144 offset:3072
	ds_read_b128 v[194:197], v144 offset:4096
	ds_read_b128 v[198:201], v144 offset:5120
	ds_read_b128 v[202:205], v144 offset:6144
	ds_read_b128 v[210:213], v144 offset:7168
	s_waitcnt vmcnt(8)
	s_waitcnt lgkmcnt(0)
	s_setprio 1
	s_barrier
	v_mfma_f32_16x16x32_bf16 v[128:131], v[146:149], v[178:181], v[128:131]
	v_mfma_f32_16x16x32_bf16 v[124:127], v[154:157], v[178:181], v[124:127]
	v_mfma_f32_16x16x32_bf16 v[120:123], v[146:149], v[186:189], v[120:123]
	v_mfma_f32_16x16x32_bf16 v[116:119], v[154:157], v[186:189], v[116:119]
	v_mfma_f32_16x16x32_bf16 v[104:107], v[146:149], v[194:197], v[104:107]
	v_mfma_f32_16x16x32_bf16 v[100:103], v[154:157], v[194:197], v[100:103]
	v_mfma_f32_16x16x32_bf16 v[88:91], v[146:149], v[202:205], v[88:91]
	v_mfma_f32_16x16x32_bf16 v[84:87], v[154:157], v[202:205], v[84:87]
	v_mfma_f32_16x16x32_bf16 v[128:131], v[150:153], v[182:185], v[128:131]
	v_mfma_f32_16x16x32_bf16 v[124:127], v[158:161], v[182:185], v[124:127]
	v_mfma_f32_16x16x32_bf16 v[120:123], v[150:153], v[190:193], v[120:123]
	v_mfma_f32_16x16x32_bf16 v[116:119], v[158:161], v[190:193], v[116:119]
	v_mfma_f32_16x16x32_bf16 v[104:107], v[150:153], v[198:201], v[104:107]
	v_mfma_f32_16x16x32_bf16 v[100:103], v[158:161], v[198:201], v[100:103]
	v_mfma_f32_16x16x32_bf16 v[88:91], v[150:153], v[210:213], v[88:91]
	v_mfma_f32_16x16x32_bf16 v[84:87], v[158:161], v[210:213], v[84:87]
	v_mfma_f32_16x16x32_bf16 v[112:115], v[162:165], v[178:181], v[112:115]
	v_mfma_f32_16x16x32_bf16 v[108:111], v[170:173], v[178:181], v[108:111]
	v_mfma_f32_16x16x32_bf16 v[96:99], v[162:165], v[186:189], v[96:99]
	v_mfma_f32_16x16x32_bf16 v[92:95], v[170:173], v[186:189], v[92:95]
	v_mfma_f32_16x16x32_bf16 v[80:83], v[162:165], v[194:197], v[80:83]
	v_mfma_f32_16x16x32_bf16 v[76:79], v[170:173], v[194:197], v[76:79]
	v_mfma_f32_16x16x32_bf16 v[72:75], v[162:165], v[202:205], v[72:75]
	v_mfma_f32_16x16x32_bf16 v[68:71], v[170:173], v[202:205], v[68:71]
	v_mfma_f32_16x16x32_bf16 v[112:115], v[166:169], v[182:185], v[112:115]
	v_mfma_f32_16x16x32_bf16 v[108:111], v[174:177], v[182:185], v[108:111]
	v_mfma_f32_16x16x32_bf16 v[96:99], v[166:169], v[190:193], v[96:99]
	v_mfma_f32_16x16x32_bf16 v[92:95], v[174:177], v[190:193], v[92:95]
	v_mfma_f32_16x16x32_bf16 v[80:83], v[166:169], v[198:201], v[80:83]
	v_mfma_f32_16x16x32_bf16 v[76:79], v[174:177], v[198:201], v[76:79]
	v_mfma_f32_16x16x32_bf16 v[72:75], v[166:169], v[210:213], v[72:75]
	v_mfma_f32_16x16x32_bf16 v[68:71], v[174:177], v[210:213], v[68:71]
	s_barrier
	s_setprio 0
	s_add_i32 s55, s33, s13
	s_mov_b32 m0, s55
	s_nop 0
	global_load_lds_dwordx4 v2, s[86:87]
	s_add_i32 m0, s55, 0x2000
	s_add_u32 s62, s86, 0x200000
	s_addc_u32 s63, s87, 0
	s_add_i32 s55, s96, s13
	global_load_lds_dwordx4 v136, s[86:87]
	s_mov_b32 m0, s55
	s_nop 0
	global_load_lds_dwordx4 v2, s[62:63]
	s_add_i32 m0, s55, 0x2000
	s_nop 0
	global_load_lds_dwordx4 v136, s[62:63]
	s_mov_b32 m0, s16
	s_nop 0
	global_load_lds_dwordx4 v132, s[88:89]
	s_mov_b32 m0, s17
	s_nop 0
	global_load_lds_dwordx4 v134, s[88:89]
	ds_read_b128 v[178:181], v144 offset:16384
	ds_read_b128 v[182:185], v144 offset:17408
	ds_read_b128 v[186:189], v144 offset:18432
	ds_read_b128 v[190:193], v144 offset:19456
	ds_read_b128 v[194:197], v144 offset:20480
	ds_read_b128 v[198:201], v144 offset:21504
	ds_read_b128 v[202:205], v144 offset:22528
	ds_read_b128 v[210:213], v144 offset:23552
	s_waitcnt vmcnt(8)
	s_waitcnt lgkmcnt(0)
	s_setprio 1
	s_barrier
	v_mfma_f32_16x16x32_bf16 v[64:67], v[146:149], v[178:181], v[64:67]
	v_mfma_f32_16x16x32_bf16 v[60:63], v[154:157], v[178:181], v[60:63]
	v_mfma_f32_16x16x32_bf16 v[56:59], v[146:149], v[186:189], v[56:59]
	v_mfma_f32_16x16x32_bf16 v[52:55], v[154:157], v[186:189], v[52:55]
	v_mfma_f32_16x16x32_bf16 v[40:43], v[146:149], v[194:197], v[40:43]
	v_mfma_f32_16x16x32_bf16 v[36:39], v[154:157], v[194:197], v[36:39]
	v_mfma_f32_16x16x32_bf16 v[24:27], v[146:149], v[202:205], v[24:27]
	v_mfma_f32_16x16x32_bf16 v[20:23], v[154:157], v[202:205], v[20:23]
	v_mfma_f32_16x16x32_bf16 v[64:67], v[150:153], v[182:185], v[64:67]
	v_mfma_f32_16x16x32_bf16 v[60:63], v[158:161], v[182:185], v[60:63]
	v_mfma_f32_16x16x32_bf16 v[56:59], v[150:153], v[190:193], v[56:59]
	v_mfma_f32_16x16x32_bf16 v[52:55], v[158:161], v[190:193], v[52:55]
	v_mfma_f32_16x16x32_bf16 v[40:43], v[150:153], v[198:201], v[40:43]
	v_mfma_f32_16x16x32_bf16 v[36:39], v[158:161], v[198:201], v[36:39]
	v_mfma_f32_16x16x32_bf16 v[24:27], v[150:153], v[210:213], v[24:27]
	v_mfma_f32_16x16x32_bf16 v[20:23], v[158:161], v[210:213], v[20:23]
	v_mfma_f32_16x16x32_bf16 v[48:51], v[162:165], v[178:181], v[48:51]
	v_mfma_f32_16x16x32_bf16 v[44:47], v[170:173], v[178:181], v[44:47]
	v_mfma_f32_16x16x32_bf16 v[32:35], v[162:165], v[186:189], v[32:35]
	v_mfma_f32_16x16x32_bf16 v[28:31], v[170:173], v[186:189], v[28:31]
	v_mfma_f32_16x16x32_bf16 v[16:19], v[162:165], v[194:197], v[16:19]
	v_mfma_f32_16x16x32_bf16 v[12:15], v[170:173], v[194:197], v[12:15]
	v_mfma_f32_16x16x32_bf16 v[8:11], v[162:165], v[202:205], v[8:11]
	v_mfma_f32_16x16x32_bf16 v[4:7], v[170:173], v[202:205], v[4:7]
	v_mfma_f32_16x16x32_bf16 v[48:51], v[166:169], v[182:185], v[48:51]
	v_mfma_f32_16x16x32_bf16 v[44:47], v[174:177], v[182:185], v[44:47]
	v_mfma_f32_16x16x32_bf16 v[32:35], v[166:169], v[190:193], v[32:35]
	v_mfma_f32_16x16x32_bf16 v[28:31], v[174:177], v[190:193], v[28:31]
	v_mfma_f32_16x16x32_bf16 v[16:19], v[166:169], v[198:201], v[16:19]
	v_mfma_f32_16x16x32_bf16 v[12:15], v[174:177], v[198:201], v[12:15]
	v_mfma_f32_16x16x32_bf16 v[8:11], v[166:169], v[210:213], v[8:11]
	v_mfma_f32_16x16x32_bf16 v[4:7], v[174:177], v[210:213], v[4:7]
	s_barrier
	s_setprio 0
	s_add_u32 s62, s88, 0x200000
	s_addc_u32 s63, s89, 0
	s_mov_b32 m0, s58
	s_nop 0
	global_load_lds_dwordx4 v132, s[62:63]
	s_mov_b32 m0, s59
	s_nop 0
	global_load_lds_dwordx4 v134, s[62:63]
	ds_read_b128 v[146:149], v248
	ds_read_b128 v[150:153], v248 offset:1024
	ds_read_b128 v[154:157], v248 offset:2048
	ds_read_b128 v[158:161], v248 offset:3072
	ds_read_b128 v[162:165], v249
	ds_read_b128 v[166:169], v249 offset:1024
	ds_read_b128 v[170:173], v249 offset:2048
	ds_read_b128 v[174:177], v249 offset:3072
	ds_read_b128 v[178:181], v144 offset:32768
	ds_read_b128 v[182:185], v144 offset:33792
	ds_read_b128 v[186:189], v144 offset:34816
	ds_read_b128 v[190:193], v144 offset:35840
	ds_read_b128 v[194:197], v144 offset:36864
	ds_read_b128 v[198:201], v144 offset:37888
	ds_read_b128 v[202:205], v144 offset:38912
	ds_read_b128 v[210:213], v144 offset:39936
	s_waitcnt vmcnt(8)
	s_waitcnt lgkmcnt(0)
	s_setprio 1
	s_barrier
	v_mfma_f32_16x16x32_bf16 v[128:131], v[146:149], v[178:181], v[128:131]
	v_mfma_f32_16x16x32_bf16 v[124:127], v[154:157], v[178:181], v[124:127]
	v_mfma_f32_16x16x32_bf16 v[120:123], v[146:149], v[186:189], v[120:123]
	v_mfma_f32_16x16x32_bf16 v[116:119], v[154:157], v[186:189], v[116:119]
	v_mfma_f32_16x16x32_bf16 v[104:107], v[146:149], v[194:197], v[104:107]
	v_mfma_f32_16x16x32_bf16 v[100:103], v[154:157], v[194:197], v[100:103]
	v_mfma_f32_16x16x32_bf16 v[88:91], v[146:149], v[202:205], v[88:91]
	v_mfma_f32_16x16x32_bf16 v[84:87], v[154:157], v[202:205], v[84:87]
	v_mfma_f32_16x16x32_bf16 v[128:131], v[150:153], v[182:185], v[128:131]
	v_mfma_f32_16x16x32_bf16 v[124:127], v[158:161], v[182:185], v[124:127]
	v_mfma_f32_16x16x32_bf16 v[120:123], v[150:153], v[190:193], v[120:123]
	v_mfma_f32_16x16x32_bf16 v[116:119], v[158:161], v[190:193], v[116:119]
	v_mfma_f32_16x16x32_bf16 v[104:107], v[150:153], v[198:201], v[104:107]
	v_mfma_f32_16x16x32_bf16 v[100:103], v[158:161], v[198:201], v[100:103]
	v_mfma_f32_16x16x32_bf16 v[88:91], v[150:153], v[210:213], v[88:91]
	v_mfma_f32_16x16x32_bf16 v[84:87], v[158:161], v[210:213], v[84:87]
	v_mfma_f32_16x16x32_bf16 v[112:115], v[162:165], v[178:181], v[112:115]
	v_mfma_f32_16x16x32_bf16 v[108:111], v[170:173], v[178:181], v[108:111]
	v_mfma_f32_16x16x32_bf16 v[96:99], v[162:165], v[186:189], v[96:99]
	v_mfma_f32_16x16x32_bf16 v[92:95], v[170:173], v[186:189], v[92:95]
	v_mfma_f32_16x16x32_bf16 v[80:83], v[162:165], v[194:197], v[80:83]
	v_mfma_f32_16x16x32_bf16 v[76:79], v[170:173], v[194:197], v[76:79]
	v_mfma_f32_16x16x32_bf16 v[72:75], v[162:165], v[202:205], v[72:75]
	v_mfma_f32_16x16x32_bf16 v[68:71], v[170:173], v[202:205], v[68:71]
	v_mfma_f32_16x16x32_bf16 v[112:115], v[166:169], v[182:185], v[112:115]
	v_mfma_f32_16x16x32_bf16 v[108:111], v[174:177], v[182:185], v[108:111]
	v_mfma_f32_16x16x32_bf16 v[96:99], v[166:169], v[190:193], v[96:99]
	v_mfma_f32_16x16x32_bf16 v[92:95], v[174:177], v[190:193], v[92:95]
	v_mfma_f32_16x16x32_bf16 v[80:83], v[166:169], v[198:201], v[80:83]
	v_mfma_f32_16x16x32_bf16 v[76:79], v[174:177], v[198:201], v[76:79]
	v_mfma_f32_16x16x32_bf16 v[72:75], v[166:169], v[210:213], v[72:75]
	v_mfma_f32_16x16x32_bf16 v[68:71], v[174:177], v[210:213], v[68:71]
	s_barrier
	s_setprio 0
	s_add_i32 s55, s97, s13
	s_mov_b32 m0, s55
	s_nop 0
	s_add_u32 s98, s86, 0x80
	s_addc_u32 s99, s87, 0
	s_nop 0
	global_load_lds_dwordx4 v2, s[98:99]
	s_add_i32 m0, s55, 0x2000
	s_add_u32 s62, s86, 0x200080
	s_addc_u32 s63, s87, 0
	s_add_i32 s55, s48, s13
	global_load_lds_dwordx4 v136, s[98:99]
	s_mov_b32 m0, s55
	s_nop 0
	global_load_lds_dwordx4 v2, s[62:63]
	s_add_i32 m0, s55, 0x2000
	s_nop 0
	global_load_lds_dwordx4 v136, s[62:63]
	s_mov_b32 m0, s60
	s_nop 0
	s_add_u32 s98, s88, 0x80
	s_addc_u32 s99, s89, 0
	s_nop 0
	global_load_lds_dwordx4 v132, s[98:99]
	s_mov_b32 m0, s61
	s_nop 0
	global_load_lds_dwordx4 v134, s[98:99]
	ds_read_b128 v[178:181], v144 offset:49152
	ds_read_b128 v[182:185], v144 offset:50176
	ds_read_b128 v[186:189], v144 offset:51200
	ds_read_b128 v[190:193], v144 offset:52224
	ds_read_b128 v[194:197], v144 offset:53248
	ds_read_b128 v[198:201], v144 offset:54272
	ds_read_b128 v[202:205], v144 offset:55296
	ds_read_b128 v[210:213], v144 offset:56320
	s_waitcnt vmcnt(8)
	s_waitcnt lgkmcnt(0)
	s_setprio 1
	s_barrier
	v_mfma_f32_16x16x32_bf16 v[64:67], v[146:149], v[178:181], v[64:67]
	v_mfma_f32_16x16x32_bf16 v[60:63], v[154:157], v[178:181], v[60:63]
	v_mfma_f32_16x16x32_bf16 v[56:59], v[146:149], v[186:189], v[56:59]
	v_mfma_f32_16x16x32_bf16 v[52:55], v[154:157], v[186:189], v[52:55]
	v_mfma_f32_16x16x32_bf16 v[40:43], v[146:149], v[194:197], v[40:43]
	v_mfma_f32_16x16x32_bf16 v[36:39], v[154:157], v[194:197], v[36:39]
	v_mfma_f32_16x16x32_bf16 v[24:27], v[146:149], v[202:205], v[24:27]
	v_mfma_f32_16x16x32_bf16 v[20:23], v[154:157], v[202:205], v[20:23]
	v_mfma_f32_16x16x32_bf16 v[64:67], v[150:153], v[182:185], v[64:67]
	v_mfma_f32_16x16x32_bf16 v[60:63], v[158:161], v[182:185], v[60:63]
	v_mfma_f32_16x16x32_bf16 v[56:59], v[150:153], v[190:193], v[56:59]
	v_mfma_f32_16x16x32_bf16 v[52:55], v[158:161], v[190:193], v[52:55]
	v_mfma_f32_16x16x32_bf16 v[40:43], v[150:153], v[198:201], v[40:43]
	v_mfma_f32_16x16x32_bf16 v[36:39], v[158:161], v[198:201], v[36:39]
	v_mfma_f32_16x16x32_bf16 v[24:27], v[150:153], v[210:213], v[24:27]
	v_mfma_f32_16x16x32_bf16 v[20:23], v[158:161], v[210:213], v[20:23]
	v_mfma_f32_16x16x32_bf16 v[48:51], v[162:165], v[178:181], v[48:51]
	v_mfma_f32_16x16x32_bf16 v[44:47], v[170:173], v[178:181], v[44:47]
	v_mfma_f32_16x16x32_bf16 v[32:35], v[162:165], v[186:189], v[32:35]
	v_mfma_f32_16x16x32_bf16 v[28:31], v[170:173], v[186:189], v[28:31]
	v_mfma_f32_16x16x32_bf16 v[16:19], v[162:165], v[194:197], v[16:19]
	v_mfma_f32_16x16x32_bf16 v[12:15], v[170:173], v[194:197], v[12:15]
	v_mfma_f32_16x16x32_bf16 v[8:11], v[162:165], v[202:205], v[8:11]
	v_mfma_f32_16x16x32_bf16 v[4:7], v[170:173], v[202:205], v[4:7]
	v_mfma_f32_16x16x32_bf16 v[48:51], v[166:169], v[182:185], v[48:51]
	v_mfma_f32_16x16x32_bf16 v[44:47], v[174:177], v[182:185], v[44:47]
	v_mfma_f32_16x16x32_bf16 v[32:35], v[166:169], v[190:193], v[32:35]
	v_mfma_f32_16x16x32_bf16 v[28:31], v[174:177], v[190:193], v[28:31]
	v_mfma_f32_16x16x32_bf16 v[16:19], v[166:169], v[198:201], v[16:19]
	v_mfma_f32_16x16x32_bf16 v[12:15], v[174:177], v[198:201], v[12:15]
	v_mfma_f32_16x16x32_bf16 v[8:11], v[166:169], v[210:213], v[8:11]
	v_mfma_f32_16x16x32_bf16 v[4:7], v[174:177], v[210:213], v[4:7]
	s_barrier
	s_setprio 0
	s_add_u32 s84, s84, 0x100
	s_addc_u32 s85, s85, 0
	s_add_u32 s29, s29, 0x100
	s_addc_u32 s35, s35, 0
	s_cmp_ge_u32 s56, s51
	s_mov_b32 s55, s56
	s_cbranch_scc0 .LBB0_763
	s_and_b64 vcc, exec, s[68:69]
	s_cbranch_vccz .LBB0_766
	s_barrier
.LBB0_766:
	s_lshl_b32 s23, s54, 8
	s_add_i32 s29, s23, 0xffffe000
	s_cmp_eq_u32 s50, 0
	s_cselect_b32 s23, s23, s29
	s_cselect_b32 s29, s31, s27
	s_cselect_b32 s35, s30, s26
	v_lshl_or_b32 v148, s22, 8, v143
	v_add_u32_e32 v150, s23, v1
	v_mov_b32_e32 v146, s35
	v_mov_b32_e32 v147, s29
	v_ashrrev_i32_e32 v149, 31, v148
	v_ashrrev_i32_e32 v151, 31, v150
	v_lshl_add_u64 v[146:147], v[148:149], 1, v[146:147]
	v_lshlrev_b64 v[148:149], 12, v[150:151]
	v_lshl_add_u64 v[148:149], v[146:147], 0, v[148:149]
	s_mov_b32 s23, 0x80000
	s_mov_b64 s[50:51], 0x80000
	v_cvt_pk_bf16_f32 v64, v64, v65
	v_cvt_pk_bf16_f32 v65, v66, v67
	v_cvt_pk_bf16_f32 v66, v60, v61
	v_add_co_u32_e32 v60, vcc, s23, v148
	v_cvt_pk_bf16_f32 v72, v72, v73
	v_cvt_pk_bf16_f32 v73, v74, v75
	v_cvt_pk_bf16_f32 v74, v68, v69
	v_lshl_add_u64 v[68:69], v[148:149], 0, s[50:51]
	v_addc_co_u32_e32 v61, vcc, 0, v149, vcc
	v_cvt_pk_bf16_f32 v48, v48, v49
	v_cvt_pk_bf16_f32 v49, v50, v51
	v_cvt_pk_bf16_f32 v50, v44, v45
	v_cvt_pk_bf16_f32 v51, v46, v47
	s_mov_b32 s23, 0x90000
	ds_bpermute_b32 v222, v231, v48
	ds_bpermute_b32 v223, v231, v49
	ds_bpermute_b32 v224, v231, v50
	ds_bpermute_b32 v225, v231, v51
	s_mov_b64 s[50:51], 0x90000
	v_cvt_pk_bf16_f32 v112, v112, v113
	v_add_co_u32_e32 v50, vcc, s23, v148
	v_cvt_pk_bf16_f32 v113, v114, v115
	v_cvt_pk_bf16_f32 v114, v108, v109
	v_or_b32_e32 v108, 16, v150
	v_lshl_add_u64 v[48:49], v[148:149], 0, s[50:51]
	v_addc_co_u32_e32 v51, vcc, 0, v149, vcc
	v_cvt_pk_bf16_f32 v32, v32, v33
	v_cvt_pk_bf16_f32 v33, v34, v35
	v_cvt_pk_bf16_f32 v34, v28, v29
	v_cvt_pk_bf16_f32 v35, v30, v31
	s_mov_b32 s23, 0xa0000
	v_ashrrev_i32_e32 v109, 31, v108
	v_cvt_pk_bf16_f32 v96, v96, v97
	v_cvt_pk_bf16_f32 v97, v98, v99
	v_cvt_pk_bf16_f32 v98, v92, v93
	v_or_b32_e32 v92, 32, v150
	s_waitcnt lgkmcnt(0)
	global_store_dwordx4 v[68:69], v[222:225], off offset:256
	ds_bpermute_b32 v226, v231, v32
	ds_bpermute_b32 v227, v231, v33
	ds_bpermute_b32 v228, v231, v34
	ds_bpermute_b32 v229, v231, v35
	s_mov_b64 s[50:51], 0xa0000
	v_cvt_pk_bf16_f32 v115, v110, v111
	v_add_co_u32_e32 v34, vcc, s23, v148
	v_lshlrev_b64 v[108:109], 12, v[108:109]
	v_ashrrev_i32_e32 v93, 31, v92
	v_cvt_pk_bf16_f32 v80, v80, v81
	v_cvt_pk_bf16_f32 v81, v82, v83
	v_cvt_pk_bf16_f32 v82, v76, v77
	v_or_b32_e32 v76, 48, v150
	v_lshl_add_u64 v[32:33], v[148:149], 0, s[50:51]
	v_addc_co_u32_e32 v35, vcc, 0, v149, vcc
	v_cvt_pk_bf16_f32 v16, v16, v17
	v_cvt_pk_bf16_f32 v17, v18, v19
	v_cvt_pk_bf16_f32 v18, v12, v13
	v_cvt_pk_bf16_f32 v19, v14, v15
	s_mov_b32 s23, 0xb0000
	s_waitcnt lgkmcnt(0)
	global_store_dwordx4 v[48:49], v[226:229], off offset:256
	ds_bpermute_b32 v222, v231, v112
	ds_bpermute_b32 v223, v231, v113
	ds_bpermute_b32 v224, v231, v114
	ds_bpermute_b32 v225, v231, v115
	v_cvt_pk_bf16_f32 v99, v94, v95
	v_lshlrev_b64 v[92:93], 12, v[92:93]
	v_lshl_add_u64 v[112:113], v[146:147], 0, v[108:109]
	v_ashrrev_i32_e32 v77, 31, v76
	s_waitcnt lgkmcnt(0)
	global_store_dwordx4 v[148:149], v[222:225], off offset:256
	ds_bpermute_b32 v226, v231, v16
	ds_bpermute_b32 v227, v231, v17
	ds_bpermute_b32 v228, v231, v18
	ds_bpermute_b32 v229, v231, v19
	s_waitcnt lgkmcnt(0)
	global_store_dwordx4 v[32:33], v[226:229], off offset:256
	ds_bpermute_b32 v222, v231, v96
	ds_bpermute_b32 v223, v231, v97
	ds_bpermute_b32 v224, v231, v98
	ds_bpermute_b32 v225, v231, v99
	v_cvt_pk_bf16_f32 v83, v78, v79
	v_add_co_u32_e32 v18, vcc, s23, v148
	v_lshl_add_u64 v[96:97], v[146:147], 0, v[92:93]
	v_lshlrev_b64 v[76:77], 12, v[76:77]
	s_mov_b64 s[50:51], 0xb0000
	v_addc_co_u32_e32 v19, vcc, 0, v149, vcc
	v_cvt_pk_bf16_f32 v128, v128, v129
	v_cvt_pk_bf16_f32 v129, v130, v131
	v_cvt_pk_bf16_f32 v130, v124, v125
	v_cvt_pk_bf16_f32 v131, v126, v127
	v_cvt_pk_bf16_f32 v108, v120, v121
	v_cvt_pk_bf16_f32 v109, v122, v123
	v_cvt_pk_bf16_f32 v110, v116, v117
	v_cvt_pk_bf16_f32 v111, v118, v119
	v_cvt_pk_bf16_f32 v92, v104, v105
	v_cvt_pk_bf16_f32 v93, v106, v107
	v_cvt_pk_bf16_f32 v94, v100, v101
	v_cvt_pk_bf16_f32 v95, v102, v103
	s_waitcnt lgkmcnt(0)
	global_store_dwordx4 v[112:113], v[222:225], off offset:256
	ds_bpermute_b32 v226, v231, v80
	ds_bpermute_b32 v227, v231, v81
	ds_bpermute_b32 v228, v231, v82
	ds_bpermute_b32 v229, v231, v83
	v_cvt_pk_bf16_f32 v78, v84, v85
	v_cvt_pk_bf16_f32 v79, v86, v87
	v_lshl_add_u64 v[80:81], v[146:147], 0, v[76:77]
	v_cvt_pk_bf16_f32 v76, v88, v89
	v_cvt_pk_bf16_f32 v77, v90, v91
	v_cvt_pk_bf16_f32 v75, v70, v71
	v_cvt_pk_bf16_f32 v67, v62, v63
	v_cvt_pk_bf16_f32 v44, v56, v57
	v_cvt_pk_bf16_f32 v45, v58, v59
	v_cvt_pk_bf16_f32 v46, v52, v53
	v_cvt_pk_bf16_f32 v47, v54, v55
	v_cvt_pk_bf16_f32 v28, v40, v41
	v_cvt_pk_bf16_f32 v29, v42, v43
	v_cvt_pk_bf16_f32 v30, v36, v37
	v_cvt_pk_bf16_f32 v31, v38, v39
	v_lshl_add_u64 v[16:17], v[148:149], 0, s[50:51]
	v_cvt_pk_bf16_f32 v12, v24, v25
	v_cvt_pk_bf16_f32 v13, v26, v27
	v_cvt_pk_bf16_f32 v14, v20, v21
	v_cvt_pk_bf16_f32 v15, v22, v23
	v_cvt_pk_bf16_f32 v8, v8, v9
	v_cvt_pk_bf16_f32 v9, v10, v11
	v_cvt_pk_bf16_f32 v10, v4, v5
	v_cvt_pk_bf16_f32 v11, v6, v7
	s_and_b64 vcc, exec, s[0:1]
	s_mov_b64 s[0:1], -1
	s_waitcnt lgkmcnt(0)
	global_store_dwordx4 v[96:97], v[226:229], off offset:256
	ds_bpermute_b32 v222, v231, v128
	ds_bpermute_b32 v223, v231, v129
	ds_bpermute_b32 v224, v231, v130
	ds_bpermute_b32 v225, v231, v131
	s_waitcnt lgkmcnt(0)
	global_store_dwordx4 v[148:149], v[222:225], off
	ds_bpermute_b32 v226, v231, v108
	ds_bpermute_b32 v227, v231, v109
	ds_bpermute_b32 v228, v231, v110
	ds_bpermute_b32 v229, v231, v111
	s_waitcnt lgkmcnt(0)
	global_store_dwordx4 v[112:113], v[226:229], off
	ds_bpermute_b32 v222, v231, v92
	ds_bpermute_b32 v223, v231, v93
	ds_bpermute_b32 v224, v231, v94
	ds_bpermute_b32 v225, v231, v95
	s_waitcnt lgkmcnt(0)
	global_store_dwordx4 v[96:97], v[222:225], off
	ds_bpermute_b32 v226, v231, v76
	ds_bpermute_b32 v227, v231, v77
	ds_bpermute_b32 v228, v231, v78
	ds_bpermute_b32 v229, v231, v79
	s_waitcnt lgkmcnt(0)
	global_store_dwordx4 v[80:81], v[226:229], off
	ds_bpermute_b32 v222, v231, v72
	ds_bpermute_b32 v223, v231, v73
	ds_bpermute_b32 v224, v231, v74
	ds_bpermute_b32 v225, v231, v75
	s_waitcnt lgkmcnt(0)
	global_store_dwordx4 v[80:81], v[222:225], off offset:256
	ds_bpermute_b32 v226, v231, v64
	ds_bpermute_b32 v227, v231, v65
	ds_bpermute_b32 v228, v231, v66
	ds_bpermute_b32 v229, v231, v67
	s_waitcnt lgkmcnt(0)
	global_store_dwordx4 v[60:61], v[226:229], off
	ds_bpermute_b32 v222, v231, v44
	ds_bpermute_b32 v223, v231, v45
	ds_bpermute_b32 v224, v231, v46
	ds_bpermute_b32 v225, v231, v47
	s_waitcnt lgkmcnt(0)
	global_store_dwordx4 v[50:51], v[222:225], off
	ds_bpermute_b32 v226, v231, v28
	ds_bpermute_b32 v227, v231, v29
	ds_bpermute_b32 v228, v231, v30
	ds_bpermute_b32 v229, v231, v31
	s_waitcnt lgkmcnt(0)
	global_store_dwordx4 v[34:35], v[226:229], off
	ds_bpermute_b32 v222, v231, v12
	ds_bpermute_b32 v223, v231, v13
	ds_bpermute_b32 v224, v231, v14
	ds_bpermute_b32 v225, v231, v15
	s_waitcnt lgkmcnt(0)
	global_store_dwordx4 v[18:19], v[222:225], off
	ds_bpermute_b32 v226, v231, v8
	ds_bpermute_b32 v227, v231, v9
	ds_bpermute_b32 v228, v231, v10
	ds_bpermute_b32 v229, v231, v11
	s_waitcnt lgkmcnt(0)
	global_store_dwordx4 v[16:17], v[226:229], off offset:256
	s_cbranch_vccnz .LBB0_757
	s_andn2_b64 vcc, exec, s[36:37]
	s_cbranch_vccnz .LBB0_756
	s_mov_b32 s100, 1
	s_branch .LBB0_756

	.amdhsa_kernel _Z10fwd_kernel4Args
		.amdhsa_group_segment_fixed_size 0
		.amdhsa_private_segment_fixed_size 0
		.amdhsa_kernarg_size 464
		.amdhsa_user_sgpr_count 2
		.amdhsa_user_sgpr_dispatch_ptr 0
		.amdhsa_user_sgpr_queue_ptr 0
		.amdhsa_user_sgpr_kernarg_segment_ptr 1
		.amdhsa_user_sgpr_dispatch_id 0
		.amdhsa_user_sgpr_kernarg_preload_length 0
		.amdhsa_user_sgpr_kernarg_preload_offset 0
		.amdhsa_user_sgpr_private_segment_size 0
		.amdhsa_uses_dynamic_stack 0
		.amdhsa_enable_private_segment 0
		.amdhsa_system_sgpr_workgroup_id_x 1
		.amdhsa_system_sgpr_workgroup_id_y 0
		.amdhsa_system_sgpr_workgroup_id_z 0
		.amdhsa_system_sgpr_workgroup_info 0
		.amdhsa_system_vgpr_workitem_id 0
		.amdhsa_next_free_vgpr 255
		.amdhsa_next_free_sgpr 101
		.amdhsa_accum_offset 256
		.amdhsa_reserve_vcc 1
		.amdhsa_float_round_mode_32 0
		.amdhsa_float_round_mode_16_64 0
		.amdhsa_float_denorm_mode_32 3
		.amdhsa_float_denorm_mode_16_64 3
		.amdhsa_dx10_clamp 1
		.amdhsa_ieee_mode 1
		.amdhsa_fp16_overflow 0
		.amdhsa_tg_split 0
		.amdhsa_exception_fp_ieee_invalid_op 0
		.amdhsa_exception_fp_denorm_src 0
		.amdhsa_exception_fp_ieee_div_zero 0
		.amdhsa_exception_fp_ieee_overflow 0
		.amdhsa_exception_fp_ieee_underflow 0
		.amdhsa_exception_fp_ieee_inexact 0
		.amdhsa_exception_int_div_zero 0
	.end_amdhsa_kernel

amdhsa.kernels:
  - .agpr_count:     0
    .args:
      - .offset:         0
        .size:           208
        .value_kind:     by_value
      - .offset:         208
        .size:           4
        .value_kind:     hidden_block_count_x
      - .offset:         212
        .size:           4
        .value_kind:     hidden_block_count_y
      - .offset:         216
        .size:           4
        .value_kind:     hidden_block_count_z
      - .offset:         220
        .size:           2
        .value_kind:     hidden_group_size_x
      - .offset:         222
        .size:           2
        .value_kind:     hidden_group_size_y
      - .offset:         224
        .size:           2
        .value_kind:     hidden_group_size_z
      - .offset:         226
        .size:           2
        .value_kind:     hidden_remainder_x
      - .offset:         228
        .size:           2
        .value_kind:     hidden_remainder_y
      - .offset:         230
        .size:           2
        .value_kind:     hidden_remainder_z
      - .offset:         248
        .size:           8
        .value_kind:     hidden_global_offset_x
      - .offset:         256
        .size:           8
        .value_kind:     hidden_global_offset_y
      - .offset:         264
        .size:           8
        .value_kind:     hidden_global_offset_z
      - .offset:         272
        .size:           2
        .value_kind:     hidden_grid_dims
      - .offset:         328
        .size:           4
        .value_kind:     hidden_dynamic_lds_size
    .group_segment_fixed_size: 0
    .kernarg_segment_align: 8
    .kernarg_segment_size: 464
    .language:       OpenCL C
    .language_version:
      - 2
      - 0
    .max_flat_workgroup_size: 512
    .name:           _Z10fwd_kernel4Args
    .private_segment_fixed_size: 0
    .sgpr_count:     107
    .sgpr_spill_count: 185
    .symbol:         _Z10fwd_kernel4Args.kd
    .uniform_work_group_size: 1
    .uses_dynamic_stack: false
    .vgpr_count:     255
    .vgpr_spill_count: 0
    .wavefront_size: 64
